# RWKV prompt chunk: own entry without per-chunk 64-bit address set-up, batched output epilogue, on top of hand-written staging
# speedup vs baseline: 1.1403x; 1.0065x over previous
.LBB0_603:
	v_mov_b64_e32 v[38:39], v[26:27]
	v_mov_b64_e32 v[34:35], v[30:31]
	s_cmp_lt_i32 s64, 0
	v_mov_b64_e32 v[36:37], v[24:25]
	v_mov_b64_e32 v[32:33], v[28:29]
	s_cbranch_scc1 .LBB0_631
	s_and_b64 vcc, exec, s[36:37]
	s_cbranch_vccz .Lrw_fast
	v_cndmask_b32_e64 v0, 0, 1, s[68:69]
	s_mov_b32 s20, 0xc000
	v_mul_lo_u32 v36, v0, s20
	s_and_b32 s20, s64, 1
	s_mul_i32 s21, s20, 0xc000
	s_mov_b32 s65, s73
	s_add_i32 s72, s21, 0
	s_lshl_b32 s70, s20, 7
	s_lshl_b64 s[20:21], s[64:65], 5
	s_add_u32 s20, s20, s4
	s_addc_u32 s21, s21, s5
	v_lshl_add_u64 v[32:33], s[20:21], 0, v[86:87]
	v_mad_u64_u32 v[2:3], s[58:59], v32, s49, 0
	v_mov_b32_e32 v0, v3
	v_mad_u64_u32 v[34:35], s[58:59], v33, s49, v[0:1]
	v_lshlrev_b64 v[98:99], 10, v[32:33]
	v_lshl_add_u64 v[32:33], s[20:21], 0, v[92:93]
	v_mad_u64_u32 v[100:101], s[58:59], v32, s49, 0
	v_mov_b32_e32 v0, v101
	v_mov_b32_e32 v3, v34
	v_mad_u64_u32 v[34:35], s[58:59], v33, s49, v[0:1]
	v_lshlrev_b64 v[102:103], 10, v[32:33]
	v_lshl_add_u64 v[32:33], s[20:21], 0, v[94:95]
	v_mad_u64_u32 v[104:105], s[58:59], v32, s49, 0
	v_mov_b32_e32 v0, v105
	v_mov_b32_e32 v101, v34
	v_mad_u64_u32 v[34:35], s[58:59], v33, s49, v[0:1]
	v_lshlrev_b64 v[106:107], 10, v[32:33]
	v_lshl_add_u64 v[32:33], s[20:21], 0, v[96:97]
	v_mad_u64_u32 v[108:109], s[20:21], v32, s49, 0
	v_mov_b32_e32 v0, v109
	v_mov_b32_e32 v105, v34
	v_mad_u64_u32 v[34:35], s[20:21], v33, s49, v[0:1]
	v_add_u32_e32 v123, v122, v36
	v_mov_b32_e32 v109, v34
	v_lshlrev_b64 v[110:111], 10, v[32:33]
	v_add_u32_e32 v0, 0, v36
	v_mov_b64_e32 v[38:39], v[26:27]
	v_mov_b64_e32 v[34:35], v[30:31]
	v_lshl_add_u32 v124, v84, 2, s72
	v_add_u32_e32 v125, s72, v85
	v_add_u32_e32 v126, s72, v114
	v_add_u32_e32 v127, s72, v115
	v_add_u32_e32 v128, s72, v116
	v_add_u32_e32 v129, 0xb00, v0
	s_mov_b32 s65, 0
	v_add_u32_e32 v130, s70, v121
	v_mov_b64_e32 v[36:37], v[24:25]
	v_mov_b64_e32 v[32:33], v[28:29]
	s_branch .LBB0_606

.Lrw_fast:
	s_setprio 3
	s_and_b32 s89, s64, 1
	s_mul_i32 s89, s89, 0xc000
	v_lshl_add_u32 v112, s28, 5, v81
	v_lshl_add_u32 v124, v84, 2, s89
	v_lshl_add_u32 v135, v112, 2, s89
	ds_read_b128 v[76:79], v124 offset:272
	ds_read_b128 v[72:75], v124 offset:256
	ds_read_b128 v[68:71], v124 offset:512
	ds_read_b128 v[56:59], v124 offset:528
	ds_read_b32 v0, v135 offset:1280
	ds_read_b128 v[64:67], v124 offset:768
	ds_read_b128 v[60:63], v124 offset:784
	ds_read_b128 v[48:51], v124 offset:0
	ds_read_b128 v[40:43], v124 offset:16
	ds_read_b128 v[52:55], v124 offset:1040
	ds_read_b128 v[44:47], v124 offset:1024
	ds_read_b128 v[156:159], v124 offset:1808
	ds_read_b128 v[152:155], v124 offset:1792
	ds_read_b128 v[182:185], v124 offset:2048
	ds_read_b128 v[186:189], v124 offset:2064
	ds_read_b32 v160, v135 offset:2816
	ds_read_b128 v[190:193], v124 offset:2304
	ds_read_b128 v[194:197], v124 offset:2320
	ds_read_b128 v[144:147], v124 offset:1536
	ds_read_b128 v[148:151], v124 offset:1552
	ds_read_b128 v[202:205], v124 offset:2576
	ds_read_b128 v[198:201], v124 offset:2560
	s_waitcnt lgkmcnt(11)
	v_pk_mul_f32 v[76:77], v[32:33], v[76:77]
	v_pk_mul_f32 v[78:79], v[34:35], v[78:79]
	v_pk_fma_f32 v[72:73], v[36:37], v[72:73], v[76:77]
	v_pk_fma_f32 v[74:75], v[38:39], v[74:75], v[78:79]
	v_pk_add_f32 v[72:73], v[72:73], v[74:75]
	v_add_f32_e32 v142, v72, v73
	s_nop 1
	v_add_f32_dpp v142, v142, v142 quad_perm:[1,0,3,2] row_mask:0xf bank_mask:0xf bound_ctrl:1
	s_nop 1
	v_add_f32_dpp v142, v142, v142 quad_perm:[2,3,0,1] row_mask:0xf bank_mask:0xf bound_ctrl:1
	s_nop 1
	v_add_f32_dpp v142, v142, v142 row_half_mirror row_mask:0xf bank_mask:0xf bound_ctrl:1
	v_pk_mul_f32 v[68:69], v[68:69], v[142:143] op_sel_hi:[1,0]
	v_pk_mul_f32 v[70:71], v[70:71], v[142:143] op_sel_hi:[1,0]
	v_pk_mul_f32 v[56:57], v[56:57], v[142:143] op_sel_hi:[1,0]
	v_pk_mul_f32 v[58:59], v[58:59], v[142:143] op_sel_hi:[1,0]
	v_pk_fma_f32 v[64:65], v[64:65], v[0:1], v[68:69] op_sel_hi:[1,0,1] neg_lo:[0,0,1] neg_hi:[0,0,1]
	v_pk_fma_f32 v[66:67], v[66:67], v[0:1], v[70:71] op_sel_hi:[1,0,1] neg_lo:[0,0,1] neg_hi:[0,0,1]
	v_pk_fma_f32 v[60:61], v[60:61], v[0:1], v[56:57] op_sel_hi:[1,0,1] neg_lo:[0,0,1] neg_hi:[0,0,1]
	v_pk_fma_f32 v[62:63], v[62:63], v[0:1], v[58:59] op_sel_hi:[1,0,1] neg_lo:[0,0,1] neg_hi:[0,0,1]
	v_pk_fma_f32 v[36:37], v[36:37], v[48:49], v[64:65]
	v_pk_fma_f32 v[38:39], v[38:39], v[50:51], v[66:67]
	v_pk_fma_f32 v[32:33], v[32:33], v[40:41], v[60:61]
	v_pk_fma_f32 v[34:35], v[34:35], v[42:43], v[62:63]
	s_waitcnt lgkmcnt(2)
	v_pk_mul_f32 v[156:157], v[32:33], v[156:157]
	v_pk_mul_f32 v[52:53], v[32:33], v[52:53]
	v_pk_mul_f32 v[158:159], v[34:35], v[158:159]
	v_pk_mul_f32 v[54:55], v[34:35], v[54:55]
	v_pk_fma_f32 v[152:153], v[36:37], v[152:153], v[156:157]
	v_pk_fma_f32 v[44:45], v[36:37], v[44:45], v[52:53]
	v_pk_fma_f32 v[154:155], v[38:39], v[154:155], v[158:159]
	v_pk_fma_f32 v[46:47], v[38:39], v[46:47], v[54:55]
	v_pk_add_f32 v[152:153], v[152:153], v[154:155]
	v_pk_add_f32 v[44:45], v[44:45], v[46:47]
	v_add_f32_e32 v142, v152, v153
	v_add_f32_e32 v143, v44, v45
	ds_read_b128 v[76:79], v124 offset:3344
	v_add_f32_dpp v142, v142, v142 quad_perm:[1,0,3,2] row_mask:0xf bank_mask:0xf bound_ctrl:1
	v_add_f32_dpp v143, v143, v143 quad_perm:[1,0,3,2] row_mask:0xf bank_mask:0xf bound_ctrl:1
	ds_read_b128 v[72:75], v124 offset:3328
	v_add_f32_dpp v142, v142, v142 quad_perm:[2,3,0,1] row_mask:0xf bank_mask:0xf bound_ctrl:1
	v_add_f32_dpp v143, v143, v143 quad_perm:[2,3,0,1] row_mask:0xf bank_mask:0xf bound_ctrl:1
	ds_read_b128 v[68:71], v124 offset:3584
	v_add_f32_dpp v142, v142, v142 row_half_mirror row_mask:0xf bank_mask:0xf bound_ctrl:1
	v_add_f32_dpp v143, v143, v143 row_half_mirror row_mask:0xf bank_mask:0xf bound_ctrl:1
	ds_read_b128 v[56:59], v124 offset:3600
	ds_read_b32 v0, v135 offset:4352
	ds_read_b128 v[64:67], v124 offset:3840
	ds_read_b128 v[60:63], v124 offset:3856
	ds_read_b128 v[48:51], v124 offset:3072
	ds_read_b128 v[40:43], v124 offset:3088
	v_pk_mul_f32 v[182:183], v[182:183], v[142:143] op_sel_hi:[1,0]
	v_pk_mul_f32 v[184:185], v[184:185], v[142:143] op_sel_hi:[1,0]
	s_mov_b32 vcc_lo, 0x1010101
	v_pk_mul_f32 v[186:187], v[186:187], v[142:143] op_sel_hi:[1,0]
	v_pk_mul_f32 v[188:189], v[188:189], v[142:143] op_sel_hi:[1,0]
	s_mov_b32 vcc_hi, 0x1010101
	v_pk_fma_f32 v[190:191], v[190:191], v[160:161], v[182:183] op_sel_hi:[1,0,1] neg_lo:[0,0,1] neg_hi:[0,0,1]
	v_pk_fma_f32 v[192:193], v[192:193], v[160:161], v[184:185] op_sel_hi:[1,0,1] neg_lo:[0,0,1] neg_hi:[0,0,1]
	v_cndmask_b32_e32 v134, v134, v143, vcc
	v_pk_fma_f32 v[194:195], v[194:195], v[160:161], v[186:187] op_sel_hi:[1,0,1] neg_lo:[0,0,1] neg_hi:[0,0,1]
	v_pk_fma_f32 v[196:197], v[196:197], v[160:161], v[188:189] op_sel_hi:[1,0,1] neg_lo:[0,0,1] neg_hi:[0,0,1]
	ds_read_b128 v[52:55], v124 offset:4112
	ds_read_b128 v[44:47], v124 offset:4096
	v_pk_fma_f32 v[36:37], v[36:37], v[144:145], v[190:191]
	v_pk_fma_f32 v[38:39], v[38:39], v[146:147], v[192:193]
	v_pk_fma_f32 v[32:33], v[32:33], v[148:149], v[194:195]
	v_pk_fma_f32 v[34:35], v[34:35], v[150:151], v[196:197]
	s_waitcnt lgkmcnt(2)
	v_pk_mul_f32 v[76:77], v[32:33], v[76:77]
	v_pk_mul_f32 v[202:203], v[32:33], v[202:203]
	v_pk_mul_f32 v[78:79], v[34:35], v[78:79]
	v_pk_mul_f32 v[204:205], v[34:35], v[204:205]
	v_pk_fma_f32 v[72:73], v[36:37], v[72:73], v[76:77]
	v_pk_fma_f32 v[198:199], v[36:37], v[198:199], v[202:203]
	v_pk_fma_f32 v[74:75], v[38:39], v[74:75], v[78:79]
	v_pk_fma_f32 v[200:201], v[38:39], v[200:201], v[204:205]
	v_pk_add_f32 v[72:73], v[72:73], v[74:75]
	v_pk_add_f32 v[198:199], v[198:199], v[200:201]
	v_add_f32_e32 v142, v72, v73
	v_add_f32_e32 v143, v198, v199
	ds_read_b128 v[156:159], v124 offset:4880
	v_add_f32_dpp v142, v142, v142 quad_perm:[1,0,3,2] row_mask:0xf bank_mask:0xf bound_ctrl:1
	v_add_f32_dpp v143, v143, v143 quad_perm:[1,0,3,2] row_mask:0xf bank_mask:0xf bound_ctrl:1
	ds_read_b128 v[152:155], v124 offset:4864
	v_add_f32_dpp v142, v142, v142 quad_perm:[2,3,0,1] row_mask:0xf bank_mask:0xf bound_ctrl:1
	v_add_f32_dpp v143, v143, v143 quad_perm:[2,3,0,1] row_mask:0xf bank_mask:0xf bound_ctrl:1
	ds_read_b128 v[182:185], v124 offset:5120
	v_add_f32_dpp v142, v142, v142 row_half_mirror row_mask:0xf bank_mask:0xf bound_ctrl:1
	v_add_f32_dpp v143, v143, v143 row_half_mirror row_mask:0xf bank_mask:0xf bound_ctrl:1
	ds_read_b128 v[186:189], v124 offset:5136
	ds_read_b32 v160, v135 offset:5888
	ds_read_b128 v[190:193], v124 offset:5376
	ds_read_b128 v[194:197], v124 offset:5392
	ds_read_b128 v[144:147], v124 offset:4608
	ds_read_b128 v[148:151], v124 offset:4624
	v_pk_mul_f32 v[68:69], v[68:69], v[142:143] op_sel_hi:[1,0]
	v_pk_mul_f32 v[70:71], v[70:71], v[142:143] op_sel_hi:[1,0]
	s_mov_b32 vcc_lo, 0x2020202
	v_pk_mul_f32 v[56:57], v[56:57], v[142:143] op_sel_hi:[1,0]
	v_pk_mul_f32 v[58:59], v[58:59], v[142:143] op_sel_hi:[1,0]
	s_mov_b32 vcc_hi, 0x2020202
	v_pk_fma_f32 v[64:65], v[64:65], v[0:1], v[68:69] op_sel_hi:[1,0,1] neg_lo:[0,0,1] neg_hi:[0,0,1]
	v_pk_fma_f32 v[66:67], v[66:67], v[0:1], v[70:71] op_sel_hi:[1,0,1] neg_lo:[0,0,1] neg_hi:[0,0,1]
	v_cndmask_b32_e32 v134, v134, v143, vcc
	v_pk_fma_f32 v[60:61], v[60:61], v[0:1], v[56:57] op_sel_hi:[1,0,1] neg_lo:[0,0,1] neg_hi:[0,0,1]
	v_pk_fma_f32 v[62:63], v[62:63], v[0:1], v[58:59] op_sel_hi:[1,0,1] neg_lo:[0,0,1] neg_hi:[0,0,1]
	ds_read_b128 v[202:205], v124 offset:5648
	ds_read_b128 v[198:201], v124 offset:5632
	v_pk_fma_f32 v[36:37], v[36:37], v[48:49], v[64:65]
	v_pk_fma_f32 v[38:39], v[38:39], v[50:51], v[66:67]
	v_pk_fma_f32 v[32:33], v[32:33], v[40:41], v[60:61]
	v_pk_fma_f32 v[34:35], v[34:35], v[42:43], v[62:63]
	s_waitcnt lgkmcnt(2)
	v_pk_mul_f32 v[156:157], v[32:33], v[156:157]
	v_pk_mul_f32 v[52:53], v[32:33], v[52:53]
	v_pk_mul_f32 v[158:159], v[34:35], v[158:159]
	v_pk_mul_f32 v[54:55], v[34:35], v[54:55]
	v_pk_fma_f32 v[152:153], v[36:37], v[152:153], v[156:157]
	v_pk_fma_f32 v[44:45], v[36:37], v[44:45], v[52:53]
	v_pk_fma_f32 v[154:155], v[38:39], v[154:155], v[158:159]
	v_pk_fma_f32 v[46:47], v[38:39], v[46:47], v[54:55]
	v_pk_add_f32 v[152:153], v[152:153], v[154:155]
	v_pk_add_f32 v[44:45], v[44:45], v[46:47]
	v_add_f32_e32 v142, v152, v153
	v_add_f32_e32 v143, v44, v45
	ds_read_b128 v[76:79], v124 offset:6416
	v_add_f32_dpp v142, v142, v142 quad_perm:[1,0,3,2] row_mask:0xf bank_mask:0xf bound_ctrl:1
	v_add_f32_dpp v143, v143, v143 quad_perm:[1,0,3,2] row_mask:0xf bank_mask:0xf bound_ctrl:1
	ds_read_b128 v[72:75], v124 offset:6400
	v_add_f32_dpp v142, v142, v142 quad_perm:[2,3,0,1] row_mask:0xf bank_mask:0xf bound_ctrl:1
	v_add_f32_dpp v143, v143, v143 quad_perm:[2,3,0,1] row_mask:0xf bank_mask:0xf bound_ctrl:1
	ds_read_b128 v[68:71], v124 offset:6656
	v_add_f32_dpp v142, v142, v142 row_half_mirror row_mask:0xf bank_mask:0xf bound_ctrl:1
	v_add_f32_dpp v143, v143, v143 row_half_mirror row_mask:0xf bank_mask:0xf bound_ctrl:1
	ds_read_b128 v[56:59], v124 offset:6672
	ds_read_b32 v0, v135 offset:7424
	ds_read_b128 v[64:67], v124 offset:6912
	ds_read_b128 v[60:63], v124 offset:6928
	ds_read_b128 v[48:51], v124 offset:6144
	ds_read_b128 v[40:43], v124 offset:6160
	v_pk_mul_f32 v[182:183], v[182:183], v[142:143] op_sel_hi:[1,0]
	v_pk_mul_f32 v[184:185], v[184:185], v[142:143] op_sel_hi:[1,0]
	s_mov_b32 vcc_lo, 0x4040404
	v_pk_mul_f32 v[186:187], v[186:187], v[142:143] op_sel_hi:[1,0]
	v_pk_mul_f32 v[188:189], v[188:189], v[142:143] op_sel_hi:[1,0]
	s_mov_b32 vcc_hi, 0x4040404
	v_pk_fma_f32 v[190:191], v[190:191], v[160:161], v[182:183] op_sel_hi:[1,0,1] neg_lo:[0,0,1] neg_hi:[0,0,1]
	v_pk_fma_f32 v[192:193], v[192:193], v[160:161], v[184:185] op_sel_hi:[1,0,1] neg_lo:[0,0,1] neg_hi:[0,0,1]
	v_cndmask_b32_e32 v134, v134, v143, vcc
	v_pk_fma_f32 v[194:195], v[194:195], v[160:161], v[186:187] op_sel_hi:[1,0,1] neg_lo:[0,0,1] neg_hi:[0,0,1]
	v_pk_fma_f32 v[196:197], v[196:197], v[160:161], v[188:189] op_sel_hi:[1,0,1] neg_lo:[0,0,1] neg_hi:[0,0,1]
	ds_read_b128 v[52:55], v124 offset:7184
	ds_read_b128 v[44:47], v124 offset:7168
	v_pk_fma_f32 v[36:37], v[36:37], v[144:145], v[190:191]
	v_pk_fma_f32 v[38:39], v[38:39], v[146:147], v[192:193]
	v_pk_fma_f32 v[32:33], v[32:33], v[148:149], v[194:195]
	v_pk_fma_f32 v[34:35], v[34:35], v[150:151], v[196:197]
	s_waitcnt lgkmcnt(2)
	v_pk_mul_f32 v[76:77], v[32:33], v[76:77]
	v_pk_mul_f32 v[202:203], v[32:33], v[202:203]
	v_pk_mul_f32 v[78:79], v[34:35], v[78:79]
	v_pk_mul_f32 v[204:205], v[34:35], v[204:205]
	v_pk_fma_f32 v[72:73], v[36:37], v[72:73], v[76:77]
	v_pk_fma_f32 v[198:199], v[36:37], v[198:199], v[202:203]
	v_pk_fma_f32 v[74:75], v[38:39], v[74:75], v[78:79]
	v_pk_fma_f32 v[200:201], v[38:39], v[200:201], v[204:205]
	v_pk_add_f32 v[72:73], v[72:73], v[74:75]
	v_pk_add_f32 v[198:199], v[198:199], v[200:201]
	v_add_f32_e32 v142, v72, v73
	v_add_f32_e32 v143, v198, v199
	ds_read_b128 v[156:159], v124 offset:7952
	v_add_f32_dpp v142, v142, v142 quad_perm:[1,0,3,2] row_mask:0xf bank_mask:0xf bound_ctrl:1
	v_add_f32_dpp v143, v143, v143 quad_perm:[1,0,3,2] row_mask:0xf bank_mask:0xf bound_ctrl:1
	ds_read_b128 v[152:155], v124 offset:7936
	v_add_f32_dpp v142, v142, v142 quad_perm:[2,3,0,1] row_mask:0xf bank_mask:0xf bound_ctrl:1
	v_add_f32_dpp v143, v143, v143 quad_perm:[2,3,0,1] row_mask:0xf bank_mask:0xf bound_ctrl:1
	ds_read_b128 v[182:185], v124 offset:8192
	v_add_f32_dpp v142, v142, v142 row_half_mirror row_mask:0xf bank_mask:0xf bound_ctrl:1
	v_add_f32_dpp v143, v143, v143 row_half_mirror row_mask:0xf bank_mask:0xf bound_ctrl:1
	ds_read_b128 v[186:189], v124 offset:8208
	ds_read_b32 v160, v135 offset:8960
	ds_read_b128 v[190:193], v124 offset:8448
	ds_read_b128 v[194:197], v124 offset:8464
	ds_read_b128 v[144:147], v124 offset:7680
	ds_read_b128 v[148:151], v124 offset:7696
	v_pk_mul_f32 v[68:69], v[68:69], v[142:143] op_sel_hi:[1,0]
	v_pk_mul_f32 v[70:71], v[70:71], v[142:143] op_sel_hi:[1,0]
	s_mov_b32 vcc_lo, 0x8080808
	v_pk_mul_f32 v[56:57], v[56:57], v[142:143] op_sel_hi:[1,0]
	v_pk_mul_f32 v[58:59], v[58:59], v[142:143] op_sel_hi:[1,0]
	s_mov_b32 vcc_hi, 0x8080808
	v_pk_fma_f32 v[64:65], v[64:65], v[0:1], v[68:69] op_sel_hi:[1,0,1] neg_lo:[0,0,1] neg_hi:[0,0,1]
	v_pk_fma_f32 v[66:67], v[66:67], v[0:1], v[70:71] op_sel_hi:[1,0,1] neg_lo:[0,0,1] neg_hi:[0,0,1]
	v_cndmask_b32_e32 v134, v134, v143, vcc
	v_pk_fma_f32 v[60:61], v[60:61], v[0:1], v[56:57] op_sel_hi:[1,0,1] neg_lo:[0,0,1] neg_hi:[0,0,1]
	v_pk_fma_f32 v[62:63], v[62:63], v[0:1], v[58:59] op_sel_hi:[1,0,1] neg_lo:[0,0,1] neg_hi:[0,0,1]
	ds_read_b128 v[202:205], v124 offset:8720
	ds_read_b128 v[198:201], v124 offset:8704
	v_pk_fma_f32 v[36:37], v[36:37], v[48:49], v[64:65]
	v_pk_fma_f32 v[38:39], v[38:39], v[50:51], v[66:67]
	v_pk_fma_f32 v[32:33], v[32:33], v[40:41], v[60:61]
	v_pk_fma_f32 v[34:35], v[34:35], v[42:43], v[62:63]
	s_waitcnt lgkmcnt(2)
	v_pk_mul_f32 v[156:157], v[32:33], v[156:157]
	v_pk_mul_f32 v[52:53], v[32:33], v[52:53]
	v_pk_mul_f32 v[158:159], v[34:35], v[158:159]
	v_pk_mul_f32 v[54:55], v[34:35], v[54:55]
	v_pk_fma_f32 v[152:153], v[36:37], v[152:153], v[156:157]
	v_pk_fma_f32 v[44:45], v[36:37], v[44:45], v[52:53]
	v_pk_fma_f32 v[154:155], v[38:39], v[154:155], v[158:159]
	v_pk_fma_f32 v[46:47], v[38:39], v[46:47], v[54:55]
	v_pk_add_f32 v[152:153], v[152:153], v[154:155]
	v_pk_add_f32 v[44:45], v[44:45], v[46:47]
	v_add_f32_e32 v142, v152, v153
	v_add_f32_e32 v143, v44, v45
	ds_read_b128 v[76:79], v124 offset:9488
	v_add_f32_dpp v142, v142, v142 quad_perm:[1,0,3,2] row_mask:0xf bank_mask:0xf bound_ctrl:1
	v_add_f32_dpp v143, v143, v143 quad_perm:[1,0,3,2] row_mask:0xf bank_mask:0xf bound_ctrl:1
	ds_read_b128 v[72:75], v124 offset:9472
	v_add_f32_dpp v142, v142, v142 quad_perm:[2,3,0,1] row_mask:0xf bank_mask:0xf bound_ctrl:1
	v_add_f32_dpp v143, v143, v143 quad_perm:[2,3,0,1] row_mask:0xf bank_mask:0xf bound_ctrl:1
	ds_read_b128 v[68:71], v124 offset:9728
	v_add_f32_dpp v142, v142, v142 row_half_mirror row_mask:0xf bank_mask:0xf bound_ctrl:1
	v_add_f32_dpp v143, v143, v143 row_half_mirror row_mask:0xf bank_mask:0xf bound_ctrl:1
	ds_read_b128 v[56:59], v124 offset:9744
	ds_read_b32 v0, v135 offset:10496
	ds_read_b128 v[64:67], v124 offset:9984
	ds_read_b128 v[60:63], v124 offset:10000
	ds_read_b128 v[48:51], v124 offset:9216
	ds_read_b128 v[40:43], v124 offset:9232
	v_pk_mul_f32 v[182:183], v[182:183], v[142:143] op_sel_hi:[1,0]
	v_pk_mul_f32 v[184:185], v[184:185], v[142:143] op_sel_hi:[1,0]
	s_mov_b32 vcc_lo, 0x10101010
	v_pk_mul_f32 v[186:187], v[186:187], v[142:143] op_sel_hi:[1,0]
	v_pk_mul_f32 v[188:189], v[188:189], v[142:143] op_sel_hi:[1,0]
	s_mov_b32 vcc_hi, 0x10101010
	v_pk_fma_f32 v[190:191], v[190:191], v[160:161], v[182:183] op_sel_hi:[1,0,1] neg_lo:[0,0,1] neg_hi:[0,0,1]
	v_pk_fma_f32 v[192:193], v[192:193], v[160:161], v[184:185] op_sel_hi:[1,0,1] neg_lo:[0,0,1] neg_hi:[0,0,1]
	v_cndmask_b32_e32 v134, v134, v143, vcc
	v_pk_fma_f32 v[194:195], v[194:195], v[160:161], v[186:187] op_sel_hi:[1,0,1] neg_lo:[0,0,1] neg_hi:[0,0,1]
	v_pk_fma_f32 v[196:197], v[196:197], v[160:161], v[188:189] op_sel_hi:[1,0,1] neg_lo:[0,0,1] neg_hi:[0,0,1]
	ds_read_b128 v[52:55], v124 offset:10256
	ds_read_b128 v[44:47], v124 offset:10240
	v_pk_fma_f32 v[36:37], v[36:37], v[144:145], v[190:191]
	v_pk_fma_f32 v[38:39], v[38:39], v[146:147], v[192:193]
	v_pk_fma_f32 v[32:33], v[32:33], v[148:149], v[194:195]
	v_pk_fma_f32 v[34:35], v[34:35], v[150:151], v[196:197]
	s_waitcnt lgkmcnt(2)
	v_pk_mul_f32 v[76:77], v[32:33], v[76:77]
	v_pk_mul_f32 v[202:203], v[32:33], v[202:203]
	v_pk_mul_f32 v[78:79], v[34:35], v[78:79]
	v_pk_mul_f32 v[204:205], v[34:35], v[204:205]
	v_pk_fma_f32 v[72:73], v[36:37], v[72:73], v[76:77]
	v_pk_fma_f32 v[198:199], v[36:37], v[198:199], v[202:203]
	v_pk_fma_f32 v[74:75], v[38:39], v[74:75], v[78:79]
	v_pk_fma_f32 v[200:201], v[38:39], v[200:201], v[204:205]
	v_pk_add_f32 v[72:73], v[72:73], v[74:75]
	v_pk_add_f32 v[198:199], v[198:199], v[200:201]
	v_add_f32_e32 v142, v72, v73
	v_add_f32_e32 v143, v198, v199
	ds_read_b128 v[156:159], v124 offset:11024
	v_add_f32_dpp v142, v142, v142 quad_perm:[1,0,3,2] row_mask:0xf bank_mask:0xf bound_ctrl:1
	v_add_f32_dpp v143, v143, v143 quad_perm:[1,0,3,2] row_mask:0xf bank_mask:0xf bound_ctrl:1
	ds_read_b128 v[152:155], v124 offset:11008
	v_add_f32_dpp v142, v142, v142 quad_perm:[2,3,0,1] row_mask:0xf bank_mask:0xf bound_ctrl:1
	v_add_f32_dpp v143, v143, v143 quad_perm:[2,3,0,1] row_mask:0xf bank_mask:0xf bound_ctrl:1
	ds_read_b128 v[182:185], v124 offset:11264
	v_add_f32_dpp v142, v142, v142 row_half_mirror row_mask:0xf bank_mask:0xf bound_ctrl:1
	v_add_f32_dpp v143, v143, v143 row_half_mirror row_mask:0xf bank_mask:0xf bound_ctrl:1
	ds_read_b128 v[186:189], v124 offset:11280
	ds_read_b32 v160, v135 offset:12032
	ds_read_b128 v[190:193], v124 offset:11520
	ds_read_b128 v[194:197], v124 offset:11536
	ds_read_b128 v[144:147], v124 offset:10752
	ds_read_b128 v[148:151], v124 offset:10768
	v_pk_mul_f32 v[68:69], v[68:69], v[142:143] op_sel_hi:[1,0]
	v_pk_mul_f32 v[70:71], v[70:71], v[142:143] op_sel_hi:[1,0]
	s_mov_b32 vcc_lo, 0x20202020
	v_pk_mul_f32 v[56:57], v[56:57], v[142:143] op_sel_hi:[1,0]
	v_pk_mul_f32 v[58:59], v[58:59], v[142:143] op_sel_hi:[1,0]
	s_mov_b32 vcc_hi, 0x20202020
	v_pk_fma_f32 v[64:65], v[64:65], v[0:1], v[68:69] op_sel_hi:[1,0,1] neg_lo:[0,0,1] neg_hi:[0,0,1]
	v_pk_fma_f32 v[66:67], v[66:67], v[0:1], v[70:71] op_sel_hi:[1,0,1] neg_lo:[0,0,1] neg_hi:[0,0,1]
	v_cndmask_b32_e32 v134, v134, v143, vcc
	v_pk_fma_f32 v[60:61], v[60:61], v[0:1], v[56:57] op_sel_hi:[1,0,1] neg_lo:[0,0,1] neg_hi:[0,0,1]
	v_pk_fma_f32 v[62:63], v[62:63], v[0:1], v[58:59] op_sel_hi:[1,0,1] neg_lo:[0,0,1] neg_hi:[0,0,1]
	ds_read_b128 v[202:205], v124 offset:11792
	ds_read_b128 v[198:201], v124 offset:11776
	v_pk_fma_f32 v[36:37], v[36:37], v[48:49], v[64:65]
	v_pk_fma_f32 v[38:39], v[38:39], v[50:51], v[66:67]
	v_pk_fma_f32 v[32:33], v[32:33], v[40:41], v[60:61]
	v_pk_fma_f32 v[34:35], v[34:35], v[42:43], v[62:63]
	s_waitcnt lgkmcnt(2)
	v_pk_mul_f32 v[156:157], v[32:33], v[156:157]
	v_pk_mul_f32 v[52:53], v[32:33], v[52:53]
	v_pk_mul_f32 v[158:159], v[34:35], v[158:159]
	v_pk_mul_f32 v[54:55], v[34:35], v[54:55]
	v_pk_fma_f32 v[152:153], v[36:37], v[152:153], v[156:157]
	v_pk_fma_f32 v[44:45], v[36:37], v[44:45], v[52:53]
	v_pk_fma_f32 v[154:155], v[38:39], v[154:155], v[158:159]
	v_pk_fma_f32 v[46:47], v[38:39], v[46:47], v[54:55]
	v_pk_add_f32 v[152:153], v[152:153], v[154:155]
	v_pk_add_f32 v[44:45], v[44:45], v[46:47]
	v_add_f32_e32 v142, v152, v153
	v_add_f32_e32 v143, v44, v45
	ds_read_b128 v[76:79], v124 offset:12560
	v_add_f32_dpp v142, v142, v142 quad_perm:[1,0,3,2] row_mask:0xf bank_mask:0xf bound_ctrl:1
	v_add_f32_dpp v143, v143, v143 quad_perm:[1,0,3,2] row_mask:0xf bank_mask:0xf bound_ctrl:1
	ds_read_b128 v[72:75], v124 offset:12544
	v_add_f32_dpp v142, v142, v142 quad_perm:[2,3,0,1] row_mask:0xf bank_mask:0xf bound_ctrl:1
	v_add_f32_dpp v143, v143, v143 quad_perm:[2,3,0,1] row_mask:0xf bank_mask:0xf bound_ctrl:1
	ds_read_b128 v[68:71], v124 offset:12800
	v_add_f32_dpp v142, v142, v142 row_half_mirror row_mask:0xf bank_mask:0xf bound_ctrl:1
	v_add_f32_dpp v143, v143, v143 row_half_mirror row_mask:0xf bank_mask:0xf bound_ctrl:1
	ds_read_b128 v[56:59], v124 offset:12816
	ds_read_b32 v0, v135 offset:13568
	ds_read_b128 v[64:67], v124 offset:13056
	ds_read_b128 v[60:63], v124 offset:13072
	ds_read_b128 v[48:51], v124 offset:12288
	ds_read_b128 v[40:43], v124 offset:12304
	v_pk_mul_f32 v[182:183], v[182:183], v[142:143] op_sel_hi:[1,0]
	v_pk_mul_f32 v[184:185], v[184:185], v[142:143] op_sel_hi:[1,0]
	s_mov_b32 vcc_lo, 0x40404040
	v_pk_mul_f32 v[186:187], v[186:187], v[142:143] op_sel_hi:[1,0]
	v_pk_mul_f32 v[188:189], v[188:189], v[142:143] op_sel_hi:[1,0]
	s_mov_b32 vcc_hi, 0x40404040
	v_pk_fma_f32 v[190:191], v[190:191], v[160:161], v[182:183] op_sel_hi:[1,0,1] neg_lo:[0,0,1] neg_hi:[0,0,1]
	v_pk_fma_f32 v[192:193], v[192:193], v[160:161], v[184:185] op_sel_hi:[1,0,1] neg_lo:[0,0,1] neg_hi:[0,0,1]
	v_cndmask_b32_e32 v134, v134, v143, vcc
	v_pk_fma_f32 v[194:195], v[194:195], v[160:161], v[186:187] op_sel_hi:[1,0,1] neg_lo:[0,0,1] neg_hi:[0,0,1]
	v_pk_fma_f32 v[196:197], v[196:197], v[160:161], v[188:189] op_sel_hi:[1,0,1] neg_lo:[0,0,1] neg_hi:[0,0,1]
	ds_read_b128 v[52:55], v124 offset:13328
	ds_read_b128 v[44:47], v124 offset:13312
	v_pk_fma_f32 v[36:37], v[36:37], v[144:145], v[190:191]
	v_pk_fma_f32 v[38:39], v[38:39], v[146:147], v[192:193]
	v_pk_fma_f32 v[32:33], v[32:33], v[148:149], v[194:195]
	v_pk_fma_f32 v[34:35], v[34:35], v[150:151], v[196:197]
	s_waitcnt lgkmcnt(2)
	v_pk_mul_f32 v[76:77], v[32:33], v[76:77]
	v_pk_mul_f32 v[202:203], v[32:33], v[202:203]
	v_pk_mul_f32 v[78:79], v[34:35], v[78:79]
	v_pk_mul_f32 v[204:205], v[34:35], v[204:205]
	v_pk_fma_f32 v[72:73], v[36:37], v[72:73], v[76:77]
	v_pk_fma_f32 v[198:199], v[36:37], v[198:199], v[202:203]
	v_pk_fma_f32 v[74:75], v[38:39], v[74:75], v[78:79]
	v_pk_fma_f32 v[200:201], v[38:39], v[200:201], v[204:205]
	v_pk_add_f32 v[72:73], v[72:73], v[74:75]
	v_pk_add_f32 v[198:199], v[198:199], v[200:201]
	v_add_f32_e32 v142, v72, v73
	v_add_f32_e32 v143, v198, v199
	ds_read_b128 v[156:159], v124 offset:14096
	v_add_f32_dpp v142, v142, v142 quad_perm:[1,0,3,2] row_mask:0xf bank_mask:0xf bound_ctrl:1
	v_add_f32_dpp v143, v143, v143 quad_perm:[1,0,3,2] row_mask:0xf bank_mask:0xf bound_ctrl:1
	ds_read_b128 v[152:155], v124 offset:14080
	v_add_f32_dpp v142, v142, v142 quad_perm:[2,3,0,1] row_mask:0xf bank_mask:0xf bound_ctrl:1
	v_add_f32_dpp v143, v143, v143 quad_perm:[2,3,0,1] row_mask:0xf bank_mask:0xf bound_ctrl:1
	ds_read_b128 v[182:185], v124 offset:14336
	v_add_f32_dpp v142, v142, v142 row_half_mirror row_mask:0xf bank_mask:0xf bound_ctrl:1
	v_add_f32_dpp v143, v143, v143 row_half_mirror row_mask:0xf bank_mask:0xf bound_ctrl:1
	ds_read_b128 v[186:189], v124 offset:14352
	ds_read_b32 v160, v135 offset:15104
	ds_read_b128 v[190:193], v124 offset:14592
	ds_read_b128 v[194:197], v124 offset:14608
	ds_read_b128 v[144:147], v124 offset:13824
	ds_read_b128 v[148:151], v124 offset:13840
	v_pk_mul_f32 v[68:69], v[68:69], v[142:143] op_sel_hi:[1,0]
	v_pk_mul_f32 v[70:71], v[70:71], v[142:143] op_sel_hi:[1,0]
	s_mov_b32 vcc_lo, 0x80808080
	v_pk_mul_f32 v[56:57], v[56:57], v[142:143] op_sel_hi:[1,0]
	v_pk_mul_f32 v[58:59], v[58:59], v[142:143] op_sel_hi:[1,0]
	s_mov_b32 vcc_hi, 0x80808080
	v_pk_fma_f32 v[64:65], v[64:65], v[0:1], v[68:69] op_sel_hi:[1,0,1] neg_lo:[0,0,1] neg_hi:[0,0,1]
	v_pk_fma_f32 v[66:67], v[66:67], v[0:1], v[70:71] op_sel_hi:[1,0,1] neg_lo:[0,0,1] neg_hi:[0,0,1]
	v_cndmask_b32_e32 v134, v134, v143, vcc
	v_pk_fma_f32 v[60:61], v[60:61], v[0:1], v[56:57] op_sel_hi:[1,0,1] neg_lo:[0,0,1] neg_hi:[0,0,1]
	v_pk_fma_f32 v[62:63], v[62:63], v[0:1], v[58:59] op_sel_hi:[1,0,1] neg_lo:[0,0,1] neg_hi:[0,0,1]
	ds_read_b128 v[202:205], v124 offset:14864
	ds_read_b128 v[198:201], v124 offset:14848
	v_pk_fma_f32 v[36:37], v[36:37], v[48:49], v[64:65]
	v_pk_fma_f32 v[38:39], v[38:39], v[50:51], v[66:67]
	v_pk_fma_f32 v[32:33], v[32:33], v[40:41], v[60:61]
	v_pk_fma_f32 v[34:35], v[34:35], v[42:43], v[62:63]
	s_waitcnt lgkmcnt(2)
	v_pk_mul_f32 v[156:157], v[32:33], v[156:157]
	v_pk_mul_f32 v[52:53], v[32:33], v[52:53]
	v_pk_mul_f32 v[158:159], v[34:35], v[158:159]
	v_pk_mul_f32 v[54:55], v[34:35], v[54:55]
	v_pk_fma_f32 v[152:153], v[36:37], v[152:153], v[156:157]
	v_pk_fma_f32 v[44:45], v[36:37], v[44:45], v[52:53]
	v_pk_fma_f32 v[154:155], v[38:39], v[154:155], v[158:159]
	v_pk_fma_f32 v[46:47], v[38:39], v[46:47], v[54:55]
	v_pk_add_f32 v[152:153], v[152:153], v[154:155]
	v_pk_add_f32 v[44:45], v[44:45], v[46:47]
	v_add_f32_e32 v142, v152, v153
	v_add_f32_e32 v143, v44, v45
	ds_read_b128 v[76:79], v124 offset:15632
	v_add_f32_dpp v142, v142, v142 quad_perm:[1,0,3,2] row_mask:0xf bank_mask:0xf bound_ctrl:1
	v_add_f32_dpp v143, v143, v143 quad_perm:[1,0,3,2] row_mask:0xf bank_mask:0xf bound_ctrl:1
	ds_read_b128 v[72:75], v124 offset:15616
	v_add_f32_dpp v142, v142, v142 quad_perm:[2,3,0,1] row_mask:0xf bank_mask:0xf bound_ctrl:1
	v_add_f32_dpp v143, v143, v143 quad_perm:[2,3,0,1] row_mask:0xf bank_mask:0xf bound_ctrl:1
	ds_read_b128 v[68:71], v124 offset:15872
	v_add_f32_dpp v142, v142, v142 row_half_mirror row_mask:0xf bank_mask:0xf bound_ctrl:1
	v_add_f32_dpp v143, v143, v143 row_half_mirror row_mask:0xf bank_mask:0xf bound_ctrl:1
	ds_read_b128 v[56:59], v124 offset:15888
	ds_read_b32 v0, v135 offset:16640
	ds_read_b128 v[64:67], v124 offset:16128
	ds_read_b128 v[60:63], v124 offset:16144
	ds_read_b128 v[48:51], v124 offset:15360
	ds_read_b128 v[40:43], v124 offset:15376
	v_pk_mul_f32 v[182:183], v[182:183], v[142:143] op_sel_hi:[1,0]
	v_pk_mul_f32 v[184:185], v[184:185], v[142:143] op_sel_hi:[1,0]
	s_mov_b32 vcc_lo, 0x1010101
	v_pk_mul_f32 v[186:187], v[186:187], v[142:143] op_sel_hi:[1,0]
	v_pk_mul_f32 v[188:189], v[188:189], v[142:143] op_sel_hi:[1,0]
	s_mov_b32 vcc_hi, 0x1010101
	v_pk_fma_f32 v[190:191], v[190:191], v[160:161], v[182:183] op_sel_hi:[1,0,1] neg_lo:[0,0,1] neg_hi:[0,0,1]
	v_pk_fma_f32 v[192:193], v[192:193], v[160:161], v[184:185] op_sel_hi:[1,0,1] neg_lo:[0,0,1] neg_hi:[0,0,1]
	v_cndmask_b32_e32 v133, v133, v143, vcc
	v_pk_fma_f32 v[194:195], v[194:195], v[160:161], v[186:187] op_sel_hi:[1,0,1] neg_lo:[0,0,1] neg_hi:[0,0,1]
	v_pk_fma_f32 v[196:197], v[196:197], v[160:161], v[188:189] op_sel_hi:[1,0,1] neg_lo:[0,0,1] neg_hi:[0,0,1]
	ds_read_b128 v[52:55], v124 offset:16400
	ds_read_b128 v[44:47], v124 offset:16384
	v_pk_fma_f32 v[36:37], v[36:37], v[144:145], v[190:191]
	v_pk_fma_f32 v[38:39], v[38:39], v[146:147], v[192:193]
	v_pk_fma_f32 v[32:33], v[32:33], v[148:149], v[194:195]
	v_pk_fma_f32 v[34:35], v[34:35], v[150:151], v[196:197]
	s_waitcnt lgkmcnt(2)
	v_pk_mul_f32 v[76:77], v[32:33], v[76:77]
	v_pk_mul_f32 v[202:203], v[32:33], v[202:203]
	v_pk_mul_f32 v[78:79], v[34:35], v[78:79]
	v_pk_mul_f32 v[204:205], v[34:35], v[204:205]
	v_pk_fma_f32 v[72:73], v[36:37], v[72:73], v[76:77]
	v_pk_fma_f32 v[198:199], v[36:37], v[198:199], v[202:203]
	v_pk_fma_f32 v[74:75], v[38:39], v[74:75], v[78:79]
	v_pk_fma_f32 v[200:201], v[38:39], v[200:201], v[204:205]
	v_pk_add_f32 v[72:73], v[72:73], v[74:75]
	v_pk_add_f32 v[198:199], v[198:199], v[200:201]
	v_add_f32_e32 v142, v72, v73
	v_add_f32_e32 v143, v198, v199
	ds_read_b128 v[156:159], v124 offset:17168
	v_add_f32_dpp v142, v142, v142 quad_perm:[1,0,3,2] row_mask:0xf bank_mask:0xf bound_ctrl:1
	v_add_f32_dpp v143, v143, v143 quad_perm:[1,0,3,2] row_mask:0xf bank_mask:0xf bound_ctrl:1
	ds_read_b128 v[152:155], v124 offset:17152
	v_add_f32_dpp v142, v142, v142 quad_perm:[2,3,0,1] row_mask:0xf bank_mask:0xf bound_ctrl:1
	v_add_f32_dpp v143, v143, v143 quad_perm:[2,3,0,1] row_mask:0xf bank_mask:0xf bound_ctrl:1
	ds_read_b128 v[182:185], v124 offset:17408
	v_add_f32_dpp v142, v142, v142 row_half_mirror row_mask:0xf bank_mask:0xf bound_ctrl:1
	v_add_f32_dpp v143, v143, v143 row_half_mirror row_mask:0xf bank_mask:0xf bound_ctrl:1
	ds_read_b128 v[186:189], v124 offset:17424
	ds_read_b32 v160, v135 offset:18176
	ds_read_b128 v[190:193], v124 offset:17664
	ds_read_b128 v[194:197], v124 offset:17680
	ds_read_b128 v[144:147], v124 offset:16896
	ds_read_b128 v[148:151], v124 offset:16912
	v_pk_mul_f32 v[68:69], v[68:69], v[142:143] op_sel_hi:[1,0]
	v_pk_mul_f32 v[70:71], v[70:71], v[142:143] op_sel_hi:[1,0]
	s_mov_b32 vcc_lo, 0x2020202
	v_pk_mul_f32 v[56:57], v[56:57], v[142:143] op_sel_hi:[1,0]
	v_pk_mul_f32 v[58:59], v[58:59], v[142:143] op_sel_hi:[1,0]
	s_mov_b32 vcc_hi, 0x2020202
	v_pk_fma_f32 v[64:65], v[64:65], v[0:1], v[68:69] op_sel_hi:[1,0,1] neg_lo:[0,0,1] neg_hi:[0,0,1]
	v_pk_fma_f32 v[66:67], v[66:67], v[0:1], v[70:71] op_sel_hi:[1,0,1] neg_lo:[0,0,1] neg_hi:[0,0,1]
	v_cndmask_b32_e32 v133, v133, v143, vcc
	v_pk_fma_f32 v[60:61], v[60:61], v[0:1], v[56:57] op_sel_hi:[1,0,1] neg_lo:[0,0,1] neg_hi:[0,0,1]
	v_pk_fma_f32 v[62:63], v[62:63], v[0:1], v[58:59] op_sel_hi:[1,0,1] neg_lo:[0,0,1] neg_hi:[0,0,1]
	ds_read_b128 v[202:205], v124 offset:17936
	ds_read_b128 v[198:201], v124 offset:17920
	v_pk_fma_f32 v[36:37], v[36:37], v[48:49], v[64:65]
	v_pk_fma_f32 v[38:39], v[38:39], v[50:51], v[66:67]
	v_pk_fma_f32 v[32:33], v[32:33], v[40:41], v[60:61]
	v_pk_fma_f32 v[34:35], v[34:35], v[42:43], v[62:63]
	s_waitcnt lgkmcnt(2)
	v_pk_mul_f32 v[156:157], v[32:33], v[156:157]
	v_pk_mul_f32 v[52:53], v[32:33], v[52:53]
	v_pk_mul_f32 v[158:159], v[34:35], v[158:159]
	v_pk_mul_f32 v[54:55], v[34:35], v[54:55]
	v_pk_fma_f32 v[152:153], v[36:37], v[152:153], v[156:157]
	v_pk_fma_f32 v[44:45], v[36:37], v[44:45], v[52:53]
	v_pk_fma_f32 v[154:155], v[38:39], v[154:155], v[158:159]
	v_pk_fma_f32 v[46:47], v[38:39], v[46:47], v[54:55]
	v_pk_add_f32 v[152:153], v[152:153], v[154:155]
	v_pk_add_f32 v[44:45], v[44:45], v[46:47]
	v_add_f32_e32 v142, v152, v153
	v_add_f32_e32 v143, v44, v45
	ds_read_b128 v[76:79], v124 offset:18704
	v_add_f32_dpp v142, v142, v142 quad_perm:[1,0,3,2] row_mask:0xf bank_mask:0xf bound_ctrl:1
	v_add_f32_dpp v143, v143, v143 quad_perm:[1,0,3,2] row_mask:0xf bank_mask:0xf bound_ctrl:1
	ds_read_b128 v[72:75], v124 offset:18688
	v_add_f32_dpp v142, v142, v142 quad_perm:[2,3,0,1] row_mask:0xf bank_mask:0xf bound_ctrl:1
	v_add_f32_dpp v143, v143, v143 quad_perm:[2,3,0,1] row_mask:0xf bank_mask:0xf bound_ctrl:1
	ds_read_b128 v[68:71], v124 offset:18944
	v_add_f32_dpp v142, v142, v142 row_half_mirror row_mask:0xf bank_mask:0xf bound_ctrl:1
	v_add_f32_dpp v143, v143, v143 row_half_mirror row_mask:0xf bank_mask:0xf bound_ctrl:1
	ds_read_b128 v[56:59], v124 offset:18960
	ds_read_b32 v0, v135 offset:19712
	ds_read_b128 v[64:67], v124 offset:19200
	ds_read_b128 v[60:63], v124 offset:19216
	ds_read_b128 v[48:51], v124 offset:18432
	ds_read_b128 v[40:43], v124 offset:18448
	v_pk_mul_f32 v[182:183], v[182:183], v[142:143] op_sel_hi:[1,0]
	v_pk_mul_f32 v[184:185], v[184:185], v[142:143] op_sel_hi:[1,0]
	s_mov_b32 vcc_lo, 0x4040404
	v_pk_mul_f32 v[186:187], v[186:187], v[142:143] op_sel_hi:[1,0]
	v_pk_mul_f32 v[188:189], v[188:189], v[142:143] op_sel_hi:[1,0]
	s_mov_b32 vcc_hi, 0x4040404
	v_pk_fma_f32 v[190:191], v[190:191], v[160:161], v[182:183] op_sel_hi:[1,0,1] neg_lo:[0,0,1] neg_hi:[0,0,1]
	v_pk_fma_f32 v[192:193], v[192:193], v[160:161], v[184:185] op_sel_hi:[1,0,1] neg_lo:[0,0,1] neg_hi:[0,0,1]
	v_cndmask_b32_e32 v133, v133, v143, vcc
	v_pk_fma_f32 v[194:195], v[194:195], v[160:161], v[186:187] op_sel_hi:[1,0,1] neg_lo:[0,0,1] neg_hi:[0,0,1]
	v_pk_fma_f32 v[196:197], v[196:197], v[160:161], v[188:189] op_sel_hi:[1,0,1] neg_lo:[0,0,1] neg_hi:[0,0,1]
	ds_read_b128 v[52:55], v124 offset:19472
	ds_read_b128 v[44:47], v124 offset:19456
	v_pk_fma_f32 v[36:37], v[36:37], v[144:145], v[190:191]
	v_pk_fma_f32 v[38:39], v[38:39], v[146:147], v[192:193]
	v_pk_fma_f32 v[32:33], v[32:33], v[148:149], v[194:195]
	v_pk_fma_f32 v[34:35], v[34:35], v[150:151], v[196:197]
	s_waitcnt lgkmcnt(2)
	v_pk_mul_f32 v[76:77], v[32:33], v[76:77]
	v_pk_mul_f32 v[202:203], v[32:33], v[202:203]
	v_pk_mul_f32 v[78:79], v[34:35], v[78:79]
	v_pk_mul_f32 v[204:205], v[34:35], v[204:205]
	v_pk_fma_f32 v[72:73], v[36:37], v[72:73], v[76:77]
	v_pk_fma_f32 v[198:199], v[36:37], v[198:199], v[202:203]
	v_pk_fma_f32 v[74:75], v[38:39], v[74:75], v[78:79]
	v_pk_fma_f32 v[200:201], v[38:39], v[200:201], v[204:205]
	v_pk_add_f32 v[72:73], v[72:73], v[74:75]
	v_pk_add_f32 v[198:199], v[198:199], v[200:201]
	v_add_f32_e32 v142, v72, v73
	v_add_f32_e32 v143, v198, v199
	ds_read_b128 v[156:159], v124 offset:20240
	v_add_f32_dpp v142, v142, v142 quad_perm:[1,0,3,2] row_mask:0xf bank_mask:0xf bound_ctrl:1
	v_add_f32_dpp v143, v143, v143 quad_perm:[1,0,3,2] row_mask:0xf bank_mask:0xf bound_ctrl:1
	ds_read_b128 v[152:155], v124 offset:20224
	v_add_f32_dpp v142, v142, v142 quad_perm:[2,3,0,1] row_mask:0xf bank_mask:0xf bound_ctrl:1
	v_add_f32_dpp v143, v143, v143 quad_perm:[2,3,0,1] row_mask:0xf bank_mask:0xf bound_ctrl:1
	ds_read_b128 v[182:185], v124 offset:20480
	v_add_f32_dpp v142, v142, v142 row_half_mirror row_mask:0xf bank_mask:0xf bound_ctrl:1
	v_add_f32_dpp v143, v143, v143 row_half_mirror row_mask:0xf bank_mask:0xf bound_ctrl:1
	ds_read_b128 v[186:189], v124 offset:20496
	ds_read_b32 v160, v135 offset:21248
	ds_read_b128 v[190:193], v124 offset:20736
	ds_read_b128 v[194:197], v124 offset:20752
	ds_read_b128 v[144:147], v124 offset:19968
	ds_read_b128 v[148:151], v124 offset:19984
	v_pk_mul_f32 v[68:69], v[68:69], v[142:143] op_sel_hi:[1,0]
	v_pk_mul_f32 v[70:71], v[70:71], v[142:143] op_sel_hi:[1,0]
	s_mov_b32 vcc_lo, 0x8080808
	v_pk_mul_f32 v[56:57], v[56:57], v[142:143] op_sel_hi:[1,0]
	v_pk_mul_f32 v[58:59], v[58:59], v[142:143] op_sel_hi:[1,0]
	s_mov_b32 vcc_hi, 0x8080808
	v_pk_fma_f32 v[64:65], v[64:65], v[0:1], v[68:69] op_sel_hi:[1,0,1] neg_lo:[0,0,1] neg_hi:[0,0,1]
	v_pk_fma_f32 v[66:67], v[66:67], v[0:1], v[70:71] op_sel_hi:[1,0,1] neg_lo:[0,0,1] neg_hi:[0,0,1]
	v_cndmask_b32_e32 v133, v133, v143, vcc
	v_pk_fma_f32 v[60:61], v[60:61], v[0:1], v[56:57] op_sel_hi:[1,0,1] neg_lo:[0,0,1] neg_hi:[0,0,1]
	v_pk_fma_f32 v[62:63], v[62:63], v[0:1], v[58:59] op_sel_hi:[1,0,1] neg_lo:[0,0,1] neg_hi:[0,0,1]
	ds_read_b128 v[202:205], v124 offset:21008
	ds_read_b128 v[198:201], v124 offset:20992
	v_pk_fma_f32 v[36:37], v[36:37], v[48:49], v[64:65]
	v_pk_fma_f32 v[38:39], v[38:39], v[50:51], v[66:67]
	v_pk_fma_f32 v[32:33], v[32:33], v[40:41], v[60:61]
	v_pk_fma_f32 v[34:35], v[34:35], v[42:43], v[62:63]
	s_waitcnt lgkmcnt(2)
	v_pk_mul_f32 v[156:157], v[32:33], v[156:157]
	v_pk_mul_f32 v[52:53], v[32:33], v[52:53]
	v_pk_mul_f32 v[158:159], v[34:35], v[158:159]
	v_pk_mul_f32 v[54:55], v[34:35], v[54:55]
	v_pk_fma_f32 v[152:153], v[36:37], v[152:153], v[156:157]
	v_pk_fma_f32 v[44:45], v[36:37], v[44:45], v[52:53]
	v_pk_fma_f32 v[154:155], v[38:39], v[154:155], v[158:159]
	v_pk_fma_f32 v[46:47], v[38:39], v[46:47], v[54:55]
	v_pk_add_f32 v[152:153], v[152:153], v[154:155]
	v_pk_add_f32 v[44:45], v[44:45], v[46:47]
	v_add_f32_e32 v142, v152, v153
	v_add_f32_e32 v143, v44, v45
	ds_read_b128 v[76:79], v124 offset:21776
	v_add_f32_dpp v142, v142, v142 quad_perm:[1,0,3,2] row_mask:0xf bank_mask:0xf bound_ctrl:1
	v_add_f32_dpp v143, v143, v143 quad_perm:[1,0,3,2] row_mask:0xf bank_mask:0xf bound_ctrl:1
	ds_read_b128 v[72:75], v124 offset:21760
	v_add_f32_dpp v142, v142, v142 quad_perm:[2,3,0,1] row_mask:0xf bank_mask:0xf bound_ctrl:1
	v_add_f32_dpp v143, v143, v143 quad_perm:[2,3,0,1] row_mask:0xf bank_mask:0xf bound_ctrl:1
	ds_read_b128 v[68:71], v124 offset:22016
	v_add_f32_dpp v142, v142, v142 row_half_mirror row_mask:0xf bank_mask:0xf bound_ctrl:1
	v_add_f32_dpp v143, v143, v143 row_half_mirror row_mask:0xf bank_mask:0xf bound_ctrl:1
	ds_read_b128 v[56:59], v124 offset:22032
	ds_read_b32 v0, v135 offset:22784
	ds_read_b128 v[64:67], v124 offset:22272
	ds_read_b128 v[60:63], v124 offset:22288
	ds_read_b128 v[48:51], v124 offset:21504
	ds_read_b128 v[40:43], v124 offset:21520
	v_pk_mul_f32 v[182:183], v[182:183], v[142:143] op_sel_hi:[1,0]
	v_pk_mul_f32 v[184:185], v[184:185], v[142:143] op_sel_hi:[1,0]
	s_mov_b32 vcc_lo, 0x10101010
	v_pk_mul_f32 v[186:187], v[186:187], v[142:143] op_sel_hi:[1,0]
	v_pk_mul_f32 v[188:189], v[188:189], v[142:143] op_sel_hi:[1,0]
	s_mov_b32 vcc_hi, 0x10101010
	v_pk_fma_f32 v[190:191], v[190:191], v[160:161], v[182:183] op_sel_hi:[1,0,1] neg_lo:[0,0,1] neg_hi:[0,0,1]
	v_pk_fma_f32 v[192:193], v[192:193], v[160:161], v[184:185] op_sel_hi:[1,0,1] neg_lo:[0,0,1] neg_hi:[0,0,1]
	v_cndmask_b32_e32 v133, v133, v143, vcc
	v_pk_fma_f32 v[194:195], v[194:195], v[160:161], v[186:187] op_sel_hi:[1,0,1] neg_lo:[0,0,1] neg_hi:[0,0,1]
	v_pk_fma_f32 v[196:197], v[196:197], v[160:161], v[188:189] op_sel_hi:[1,0,1] neg_lo:[0,0,1] neg_hi:[0,0,1]
	ds_read_b128 v[52:55], v124 offset:22544
	ds_read_b128 v[44:47], v124 offset:22528
	v_pk_fma_f32 v[36:37], v[36:37], v[144:145], v[190:191]
	v_pk_fma_f32 v[38:39], v[38:39], v[146:147], v[192:193]
	v_pk_fma_f32 v[32:33], v[32:33], v[148:149], v[194:195]
	v_pk_fma_f32 v[34:35], v[34:35], v[150:151], v[196:197]
	s_waitcnt lgkmcnt(2)
	v_pk_mul_f32 v[76:77], v[32:33], v[76:77]
	v_pk_mul_f32 v[202:203], v[32:33], v[202:203]
	v_pk_mul_f32 v[78:79], v[34:35], v[78:79]
	v_pk_mul_f32 v[204:205], v[34:35], v[204:205]
	v_pk_fma_f32 v[72:73], v[36:37], v[72:73], v[76:77]
	v_pk_fma_f32 v[198:199], v[36:37], v[198:199], v[202:203]
	v_pk_fma_f32 v[74:75], v[38:39], v[74:75], v[78:79]
	v_pk_fma_f32 v[200:201], v[38:39], v[200:201], v[204:205]
	v_pk_add_f32 v[72:73], v[72:73], v[74:75]
	v_pk_add_f32 v[198:199], v[198:199], v[200:201]
	v_add_f32_e32 v142, v72, v73
	v_add_f32_e32 v143, v198, v199
	ds_read_b128 v[156:159], v124 offset:23312
	v_add_f32_dpp v142, v142, v142 quad_perm:[1,0,3,2] row_mask:0xf bank_mask:0xf bound_ctrl:1
	v_add_f32_dpp v143, v143, v143 quad_perm:[1,0,3,2] row_mask:0xf bank_mask:0xf bound_ctrl:1
	ds_read_b128 v[152:155], v124 offset:23296
	v_add_f32_dpp v142, v142, v142 quad_perm:[2,3,0,1] row_mask:0xf bank_mask:0xf bound_ctrl:1
	v_add_f32_dpp v143, v143, v143 quad_perm:[2,3,0,1] row_mask:0xf bank_mask:0xf bound_ctrl:1
	ds_read_b128 v[182:185], v124 offset:23552
	v_add_f32_dpp v142, v142, v142 row_half_mirror row_mask:0xf bank_mask:0xf bound_ctrl:1
	v_add_f32_dpp v143, v143, v143 row_half_mirror row_mask:0xf bank_mask:0xf bound_ctrl:1
	ds_read_b128 v[186:189], v124 offset:23568
	ds_read_b32 v160, v135 offset:24320
	ds_read_b128 v[190:193], v124 offset:23808
	ds_read_b128 v[194:197], v124 offset:23824
	ds_read_b128 v[144:147], v124 offset:23040
	ds_read_b128 v[148:151], v124 offset:23056
	v_pk_mul_f32 v[68:69], v[68:69], v[142:143] op_sel_hi:[1,0]
	v_pk_mul_f32 v[70:71], v[70:71], v[142:143] op_sel_hi:[1,0]
	s_mov_b32 vcc_lo, 0x20202020
	v_pk_mul_f32 v[56:57], v[56:57], v[142:143] op_sel_hi:[1,0]
	v_pk_mul_f32 v[58:59], v[58:59], v[142:143] op_sel_hi:[1,0]
	s_mov_b32 vcc_hi, 0x20202020
	v_pk_fma_f32 v[64:65], v[64:65], v[0:1], v[68:69] op_sel_hi:[1,0,1] neg_lo:[0,0,1] neg_hi:[0,0,1]
	v_pk_fma_f32 v[66:67], v[66:67], v[0:1], v[70:71] op_sel_hi:[1,0,1] neg_lo:[0,0,1] neg_hi:[0,0,1]
	v_cndmask_b32_e32 v133, v133, v143, vcc
	v_pk_fma_f32 v[60:61], v[60:61], v[0:1], v[56:57] op_sel_hi:[1,0,1] neg_lo:[0,0,1] neg_hi:[0,0,1]
	v_pk_fma_f32 v[62:63], v[62:63], v[0:1], v[58:59] op_sel_hi:[1,0,1] neg_lo:[0,0,1] neg_hi:[0,0,1]
	ds_read_b128 v[202:205], v124 offset:24080
	ds_read_b128 v[198:201], v124 offset:24064
	v_pk_fma_f32 v[36:37], v[36:37], v[48:49], v[64:65]
	v_pk_fma_f32 v[38:39], v[38:39], v[50:51], v[66:67]
	v_pk_fma_f32 v[32:33], v[32:33], v[40:41], v[60:61]
	v_pk_fma_f32 v[34:35], v[34:35], v[42:43], v[62:63]
	s_waitcnt lgkmcnt(2)
	v_pk_mul_f32 v[156:157], v[32:33], v[156:157]
	v_pk_mul_f32 v[52:53], v[32:33], v[52:53]
	v_pk_mul_f32 v[158:159], v[34:35], v[158:159]
	v_pk_mul_f32 v[54:55], v[34:35], v[54:55]
	v_pk_fma_f32 v[152:153], v[36:37], v[152:153], v[156:157]
	v_pk_fma_f32 v[44:45], v[36:37], v[44:45], v[52:53]
	v_pk_fma_f32 v[154:155], v[38:39], v[154:155], v[158:159]
	v_pk_fma_f32 v[46:47], v[38:39], v[46:47], v[54:55]
	v_pk_add_f32 v[152:153], v[152:153], v[154:155]
	v_pk_add_f32 v[44:45], v[44:45], v[46:47]
	v_add_f32_e32 v142, v152, v153
	v_add_f32_e32 v143, v44, v45
	ds_read_b128 v[76:79], v124 offset:24848
	v_add_f32_dpp v142, v142, v142 quad_perm:[1,0,3,2] row_mask:0xf bank_mask:0xf bound_ctrl:1
	v_add_f32_dpp v143, v143, v143 quad_perm:[1,0,3,2] row_mask:0xf bank_mask:0xf bound_ctrl:1
	ds_read_b128 v[72:75], v124 offset:24832
	v_add_f32_dpp v142, v142, v142 quad_perm:[2,3,0,1] row_mask:0xf bank_mask:0xf bound_ctrl:1
	v_add_f32_dpp v143, v143, v143 quad_perm:[2,3,0,1] row_mask:0xf bank_mask:0xf bound_ctrl:1
	ds_read_b128 v[68:71], v124 offset:25088
	v_add_f32_dpp v142, v142, v142 row_half_mirror row_mask:0xf bank_mask:0xf bound_ctrl:1
	v_add_f32_dpp v143, v143, v143 row_half_mirror row_mask:0xf bank_mask:0xf bound_ctrl:1
	ds_read_b128 v[56:59], v124 offset:25104
	ds_read_b32 v0, v135 offset:25856
	ds_read_b128 v[64:67], v124 offset:25344
	ds_read_b128 v[60:63], v124 offset:25360
	ds_read_b128 v[48:51], v124 offset:24576
	ds_read_b128 v[40:43], v124 offset:24592
	v_pk_mul_f32 v[182:183], v[182:183], v[142:143] op_sel_hi:[1,0]
	v_pk_mul_f32 v[184:185], v[184:185], v[142:143] op_sel_hi:[1,0]
	s_mov_b32 vcc_lo, 0x40404040
	v_pk_mul_f32 v[186:187], v[186:187], v[142:143] op_sel_hi:[1,0]
	v_pk_mul_f32 v[188:189], v[188:189], v[142:143] op_sel_hi:[1,0]
	s_mov_b32 vcc_hi, 0x40404040
	v_pk_fma_f32 v[190:191], v[190:191], v[160:161], v[182:183] op_sel_hi:[1,0,1] neg_lo:[0,0,1] neg_hi:[0,0,1]
	v_pk_fma_f32 v[192:193], v[192:193], v[160:161], v[184:185] op_sel_hi:[1,0,1] neg_lo:[0,0,1] neg_hi:[0,0,1]
	v_cndmask_b32_e32 v133, v133, v143, vcc
	v_pk_fma_f32 v[194:195], v[194:195], v[160:161], v[186:187] op_sel_hi:[1,0,1] neg_lo:[0,0,1] neg_hi:[0,0,1]
	v_pk_fma_f32 v[196:197], v[196:197], v[160:161], v[188:189] op_sel_hi:[1,0,1] neg_lo:[0,0,1] neg_hi:[0,0,1]
	ds_read_b128 v[52:55], v124 offset:25616
	ds_read_b128 v[44:47], v124 offset:25600
	v_pk_fma_f32 v[36:37], v[36:37], v[144:145], v[190:191]
	v_pk_fma_f32 v[38:39], v[38:39], v[146:147], v[192:193]
	v_pk_fma_f32 v[32:33], v[32:33], v[148:149], v[194:195]
	v_pk_fma_f32 v[34:35], v[34:35], v[150:151], v[196:197]
	s_waitcnt lgkmcnt(2)
	v_pk_mul_f32 v[76:77], v[32:33], v[76:77]
	v_pk_mul_f32 v[202:203], v[32:33], v[202:203]
	v_pk_mul_f32 v[78:79], v[34:35], v[78:79]
	v_pk_mul_f32 v[204:205], v[34:35], v[204:205]
	v_pk_fma_f32 v[72:73], v[36:37], v[72:73], v[76:77]
	v_pk_fma_f32 v[198:199], v[36:37], v[198:199], v[202:203]
	v_pk_fma_f32 v[74:75], v[38:39], v[74:75], v[78:79]
	v_pk_fma_f32 v[200:201], v[38:39], v[200:201], v[204:205]
	v_pk_add_f32 v[72:73], v[72:73], v[74:75]
	v_pk_add_f32 v[198:199], v[198:199], v[200:201]
	v_add_f32_e32 v142, v72, v73
	v_add_f32_e32 v143, v198, v199
	ds_read_b128 v[156:159], v124 offset:26384
	v_add_f32_dpp v142, v142, v142 quad_perm:[1,0,3,2] row_mask:0xf bank_mask:0xf bound_ctrl:1
	v_add_f32_dpp v143, v143, v143 quad_perm:[1,0,3,2] row_mask:0xf bank_mask:0xf bound_ctrl:1
	ds_read_b128 v[152:155], v124 offset:26368
	v_add_f32_dpp v142, v142, v142 quad_perm:[2,3,0,1] row_mask:0xf bank_mask:0xf bound_ctrl:1
	v_add_f32_dpp v143, v143, v143 quad_perm:[2,3,0,1] row_mask:0xf bank_mask:0xf bound_ctrl:1
	ds_read_b128 v[182:185], v124 offset:26624
	v_add_f32_dpp v142, v142, v142 row_half_mirror row_mask:0xf bank_mask:0xf bound_ctrl:1
	v_add_f32_dpp v143, v143, v143 row_half_mirror row_mask:0xf bank_mask:0xf bound_ctrl:1
	ds_read_b128 v[186:189], v124 offset:26640
	ds_read_b32 v160, v135 offset:27392
	ds_read_b128 v[190:193], v124 offset:26880
	ds_read_b128 v[194:197], v124 offset:26896
	ds_read_b128 v[144:147], v124 offset:26112
	ds_read_b128 v[148:151], v124 offset:26128
	v_pk_mul_f32 v[68:69], v[68:69], v[142:143] op_sel_hi:[1,0]
	v_pk_mul_f32 v[70:71], v[70:71], v[142:143] op_sel_hi:[1,0]
	s_mov_b32 vcc_lo, 0x80808080
	v_pk_mul_f32 v[56:57], v[56:57], v[142:143] op_sel_hi:[1,0]
	v_pk_mul_f32 v[58:59], v[58:59], v[142:143] op_sel_hi:[1,0]
	s_mov_b32 vcc_hi, 0x80808080
	v_pk_fma_f32 v[64:65], v[64:65], v[0:1], v[68:69] op_sel_hi:[1,0,1] neg_lo:[0,0,1] neg_hi:[0,0,1]
	v_pk_fma_f32 v[66:67], v[66:67], v[0:1], v[70:71] op_sel_hi:[1,0,1] neg_lo:[0,0,1] neg_hi:[0,0,1]
	v_cndmask_b32_e32 v133, v133, v143, vcc
	v_pk_fma_f32 v[60:61], v[60:61], v[0:1], v[56:57] op_sel_hi:[1,0,1] neg_lo:[0,0,1] neg_hi:[0,0,1]
	v_pk_fma_f32 v[62:63], v[62:63], v[0:1], v[58:59] op_sel_hi:[1,0,1] neg_lo:[0,0,1] neg_hi:[0,0,1]
	ds_read_b128 v[202:205], v124 offset:27152
	ds_read_b128 v[198:201], v124 offset:27136
	v_pk_fma_f32 v[36:37], v[36:37], v[48:49], v[64:65]
	v_pk_fma_f32 v[38:39], v[38:39], v[50:51], v[66:67]
	v_pk_fma_f32 v[32:33], v[32:33], v[40:41], v[60:61]
	v_pk_fma_f32 v[34:35], v[34:35], v[42:43], v[62:63]
	s_waitcnt lgkmcnt(2)
	v_pk_mul_f32 v[156:157], v[32:33], v[156:157]
	v_pk_mul_f32 v[52:53], v[32:33], v[52:53]
	v_pk_mul_f32 v[158:159], v[34:35], v[158:159]
	v_pk_mul_f32 v[54:55], v[34:35], v[54:55]
	v_pk_fma_f32 v[152:153], v[36:37], v[152:153], v[156:157]
	v_pk_fma_f32 v[44:45], v[36:37], v[44:45], v[52:53]
	v_pk_fma_f32 v[154:155], v[38:39], v[154:155], v[158:159]
	v_pk_fma_f32 v[46:47], v[38:39], v[46:47], v[54:55]
	v_pk_add_f32 v[152:153], v[152:153], v[154:155]
	v_pk_add_f32 v[44:45], v[44:45], v[46:47]
	v_add_f32_e32 v142, v152, v153
	v_add_f32_e32 v143, v44, v45
	ds_read_b128 v[76:79], v124 offset:27920
	v_add_f32_dpp v142, v142, v142 quad_perm:[1,0,3,2] row_mask:0xf bank_mask:0xf bound_ctrl:1
	v_add_f32_dpp v143, v143, v143 quad_perm:[1,0,3,2] row_mask:0xf bank_mask:0xf bound_ctrl:1
	ds_read_b128 v[72:75], v124 offset:27904
	v_add_f32_dpp v142, v142, v142 quad_perm:[2,3,0,1] row_mask:0xf bank_mask:0xf bound_ctrl:1
	v_add_f32_dpp v143, v143, v143 quad_perm:[2,3,0,1] row_mask:0xf bank_mask:0xf bound_ctrl:1
	ds_read_b128 v[68:71], v124 offset:28160
	v_add_f32_dpp v142, v142, v142 row_half_mirror row_mask:0xf bank_mask:0xf bound_ctrl:1
	v_add_f32_dpp v143, v143, v143 row_half_mirror row_mask:0xf bank_mask:0xf bound_ctrl:1
	ds_read_b128 v[56:59], v124 offset:28176
	ds_read_b32 v0, v135 offset:28928
	ds_read_b128 v[64:67], v124 offset:28416
	ds_read_b128 v[60:63], v124 offset:28432
	ds_read_b128 v[48:51], v124 offset:27648
	ds_read_b128 v[40:43], v124 offset:27664
	v_pk_mul_f32 v[182:183], v[182:183], v[142:143] op_sel_hi:[1,0]
	v_pk_mul_f32 v[184:185], v[184:185], v[142:143] op_sel_hi:[1,0]
	s_mov_b32 vcc_lo, 0x1010101
	v_pk_mul_f32 v[186:187], v[186:187], v[142:143] op_sel_hi:[1,0]
	v_pk_mul_f32 v[188:189], v[188:189], v[142:143] op_sel_hi:[1,0]
	s_mov_b32 vcc_hi, 0x1010101
	v_pk_fma_f32 v[190:191], v[190:191], v[160:161], v[182:183] op_sel_hi:[1,0,1] neg_lo:[0,0,1] neg_hi:[0,0,1]
	v_pk_fma_f32 v[192:193], v[192:193], v[160:161], v[184:185] op_sel_hi:[1,0,1] neg_lo:[0,0,1] neg_hi:[0,0,1]
	v_cndmask_b32_e32 v132, v132, v143, vcc
	v_pk_fma_f32 v[194:195], v[194:195], v[160:161], v[186:187] op_sel_hi:[1,0,1] neg_lo:[0,0,1] neg_hi:[0,0,1]
	v_pk_fma_f32 v[196:197], v[196:197], v[160:161], v[188:189] op_sel_hi:[1,0,1] neg_lo:[0,0,1] neg_hi:[0,0,1]
	ds_read_b128 v[52:55], v124 offset:28688
	ds_read_b128 v[44:47], v124 offset:28672
	v_pk_fma_f32 v[36:37], v[36:37], v[144:145], v[190:191]
	v_pk_fma_f32 v[38:39], v[38:39], v[146:147], v[192:193]
	v_pk_fma_f32 v[32:33], v[32:33], v[148:149], v[194:195]
	v_pk_fma_f32 v[34:35], v[34:35], v[150:151], v[196:197]
	s_waitcnt lgkmcnt(2)
	v_pk_mul_f32 v[76:77], v[32:33], v[76:77]
	v_pk_mul_f32 v[202:203], v[32:33], v[202:203]
	v_pk_mul_f32 v[78:79], v[34:35], v[78:79]
	v_pk_mul_f32 v[204:205], v[34:35], v[204:205]
	v_pk_fma_f32 v[72:73], v[36:37], v[72:73], v[76:77]
	v_pk_fma_f32 v[198:199], v[36:37], v[198:199], v[202:203]
	v_pk_fma_f32 v[74:75], v[38:39], v[74:75], v[78:79]
	v_pk_fma_f32 v[200:201], v[38:39], v[200:201], v[204:205]
	v_pk_add_f32 v[72:73], v[72:73], v[74:75]
	v_pk_add_f32 v[198:199], v[198:199], v[200:201]
	v_add_f32_e32 v142, v72, v73
	v_add_f32_e32 v143, v198, v199
	ds_read_b128 v[156:159], v124 offset:29456
	v_add_f32_dpp v142, v142, v142 quad_perm:[1,0,3,2] row_mask:0xf bank_mask:0xf bound_ctrl:1
	v_add_f32_dpp v143, v143, v143 quad_perm:[1,0,3,2] row_mask:0xf bank_mask:0xf bound_ctrl:1
	ds_read_b128 v[152:155], v124 offset:29440
	v_add_f32_dpp v142, v142, v142 quad_perm:[2,3,0,1] row_mask:0xf bank_mask:0xf bound_ctrl:1
	v_add_f32_dpp v143, v143, v143 quad_perm:[2,3,0,1] row_mask:0xf bank_mask:0xf bound_ctrl:1
	ds_read_b128 v[182:185], v124 offset:29696
	v_add_f32_dpp v142, v142, v142 row_half_mirror row_mask:0xf bank_mask:0xf bound_ctrl:1
	v_add_f32_dpp v143, v143, v143 row_half_mirror row_mask:0xf bank_mask:0xf bound_ctrl:1
	ds_read_b128 v[186:189], v124 offset:29712
	ds_read_b32 v160, v135 offset:30464
	ds_read_b128 v[190:193], v124 offset:29952
	ds_read_b128 v[194:197], v124 offset:29968
	ds_read_b128 v[144:147], v124 offset:29184
	ds_read_b128 v[148:151], v124 offset:29200
	v_pk_mul_f32 v[68:69], v[68:69], v[142:143] op_sel_hi:[1,0]
	v_pk_mul_f32 v[70:71], v[70:71], v[142:143] op_sel_hi:[1,0]
	s_mov_b32 vcc_lo, 0x2020202
	v_pk_mul_f32 v[56:57], v[56:57], v[142:143] op_sel_hi:[1,0]
	v_pk_mul_f32 v[58:59], v[58:59], v[142:143] op_sel_hi:[1,0]
	s_mov_b32 vcc_hi, 0x2020202
	v_pk_fma_f32 v[64:65], v[64:65], v[0:1], v[68:69] op_sel_hi:[1,0,1] neg_lo:[0,0,1] neg_hi:[0,0,1]
	v_pk_fma_f32 v[66:67], v[66:67], v[0:1], v[70:71] op_sel_hi:[1,0,1] neg_lo:[0,0,1] neg_hi:[0,0,1]
	v_cndmask_b32_e32 v132, v132, v143, vcc
	v_pk_fma_f32 v[60:61], v[60:61], v[0:1], v[56:57] op_sel_hi:[1,0,1] neg_lo:[0,0,1] neg_hi:[0,0,1]
	v_pk_fma_f32 v[62:63], v[62:63], v[0:1], v[58:59] op_sel_hi:[1,0,1] neg_lo:[0,0,1] neg_hi:[0,0,1]
	ds_read_b128 v[202:205], v124 offset:30224
	ds_read_b128 v[198:201], v124 offset:30208
	v_pk_fma_f32 v[36:37], v[36:37], v[48:49], v[64:65]
	v_pk_fma_f32 v[38:39], v[38:39], v[50:51], v[66:67]
	v_pk_fma_f32 v[32:33], v[32:33], v[40:41], v[60:61]
	v_pk_fma_f32 v[34:35], v[34:35], v[42:43], v[62:63]
	s_waitcnt lgkmcnt(2)
	v_pk_mul_f32 v[156:157], v[32:33], v[156:157]
	v_pk_mul_f32 v[52:53], v[32:33], v[52:53]
	v_pk_mul_f32 v[158:159], v[34:35], v[158:159]
	v_pk_mul_f32 v[54:55], v[34:35], v[54:55]
	v_pk_fma_f32 v[152:153], v[36:37], v[152:153], v[156:157]
	v_pk_fma_f32 v[44:45], v[36:37], v[44:45], v[52:53]
	v_pk_fma_f32 v[154:155], v[38:39], v[154:155], v[158:159]
	v_pk_fma_f32 v[46:47], v[38:39], v[46:47], v[54:55]
	v_pk_add_f32 v[152:153], v[152:153], v[154:155]
	v_pk_add_f32 v[44:45], v[44:45], v[46:47]
	v_add_f32_e32 v142, v152, v153
	v_add_f32_e32 v143, v44, v45
	ds_read_b128 v[76:79], v124 offset:30992
	v_add_f32_dpp v142, v142, v142 quad_perm:[1,0,3,2] row_mask:0xf bank_mask:0xf bound_ctrl:1
	v_add_f32_dpp v143, v143, v143 quad_perm:[1,0,3,2] row_mask:0xf bank_mask:0xf bound_ctrl:1
	ds_read_b128 v[72:75], v124 offset:30976
	v_add_f32_dpp v142, v142, v142 quad_perm:[2,3,0,1] row_mask:0xf bank_mask:0xf bound_ctrl:1
	v_add_f32_dpp v143, v143, v143 quad_perm:[2,3,0,1] row_mask:0xf bank_mask:0xf bound_ctrl:1
	ds_read_b128 v[68:71], v124 offset:31232
	v_add_f32_dpp v142, v142, v142 row_half_mirror row_mask:0xf bank_mask:0xf bound_ctrl:1
	v_add_f32_dpp v143, v143, v143 row_half_mirror row_mask:0xf bank_mask:0xf bound_ctrl:1
	ds_read_b128 v[56:59], v124 offset:31248
	ds_read_b32 v0, v135 offset:32000
	ds_read_b128 v[64:67], v124 offset:31488
	ds_read_b128 v[60:63], v124 offset:31504
	ds_read_b128 v[48:51], v124 offset:30720
	ds_read_b128 v[40:43], v124 offset:30736
	v_pk_mul_f32 v[182:183], v[182:183], v[142:143] op_sel_hi:[1,0]
	v_pk_mul_f32 v[184:185], v[184:185], v[142:143] op_sel_hi:[1,0]
	s_mov_b32 vcc_lo, 0x4040404
	v_pk_mul_f32 v[186:187], v[186:187], v[142:143] op_sel_hi:[1,0]
	v_pk_mul_f32 v[188:189], v[188:189], v[142:143] op_sel_hi:[1,0]
	s_mov_b32 vcc_hi, 0x4040404
	v_pk_fma_f32 v[190:191], v[190:191], v[160:161], v[182:183] op_sel_hi:[1,0,1] neg_lo:[0,0,1] neg_hi:[0,0,1]
	v_pk_fma_f32 v[192:193], v[192:193], v[160:161], v[184:185] op_sel_hi:[1,0,1] neg_lo:[0,0,1] neg_hi:[0,0,1]
	v_cndmask_b32_e32 v132, v132, v143, vcc
	v_pk_fma_f32 v[194:195], v[194:195], v[160:161], v[186:187] op_sel_hi:[1,0,1] neg_lo:[0,0,1] neg_hi:[0,0,1]
	v_pk_fma_f32 v[196:197], v[196:197], v[160:161], v[188:189] op_sel_hi:[1,0,1] neg_lo:[0,0,1] neg_hi:[0,0,1]
	ds_read_b128 v[52:55], v124 offset:31760
	ds_read_b128 v[44:47], v124 offset:31744
	v_pk_fma_f32 v[36:37], v[36:37], v[144:145], v[190:191]
	v_pk_fma_f32 v[38:39], v[38:39], v[146:147], v[192:193]
	v_pk_fma_f32 v[32:33], v[32:33], v[148:149], v[194:195]
	v_pk_fma_f32 v[34:35], v[34:35], v[150:151], v[196:197]
	s_waitcnt lgkmcnt(2)
	v_pk_mul_f32 v[76:77], v[32:33], v[76:77]
	v_pk_mul_f32 v[202:203], v[32:33], v[202:203]
	v_pk_mul_f32 v[78:79], v[34:35], v[78:79]
	v_pk_mul_f32 v[204:205], v[34:35], v[204:205]
	v_pk_fma_f32 v[72:73], v[36:37], v[72:73], v[76:77]
	v_pk_fma_f32 v[198:199], v[36:37], v[198:199], v[202:203]
	v_pk_fma_f32 v[74:75], v[38:39], v[74:75], v[78:79]
	v_pk_fma_f32 v[200:201], v[38:39], v[200:201], v[204:205]
	v_pk_add_f32 v[72:73], v[72:73], v[74:75]
	v_pk_add_f32 v[198:199], v[198:199], v[200:201]
	v_add_f32_e32 v142, v72, v73
	v_add_f32_e32 v143, v198, v199
	ds_read_b128 v[156:159], v124 offset:32528
	v_add_f32_dpp v142, v142, v142 quad_perm:[1,0,3,2] row_mask:0xf bank_mask:0xf bound_ctrl:1
	v_add_f32_dpp v143, v143, v143 quad_perm:[1,0,3,2] row_mask:0xf bank_mask:0xf bound_ctrl:1
	ds_read_b128 v[152:155], v124 offset:32512
	v_add_f32_dpp v142, v142, v142 quad_perm:[2,3,0,1] row_mask:0xf bank_mask:0xf bound_ctrl:1
	v_add_f32_dpp v143, v143, v143 quad_perm:[2,3,0,1] row_mask:0xf bank_mask:0xf bound_ctrl:1
	ds_read_b128 v[182:185], v124 offset:32768
	v_add_f32_dpp v142, v142, v142 row_half_mirror row_mask:0xf bank_mask:0xf bound_ctrl:1
	v_add_f32_dpp v143, v143, v143 row_half_mirror row_mask:0xf bank_mask:0xf bound_ctrl:1
	ds_read_b128 v[186:189], v124 offset:32784
	ds_read_b32 v160, v135 offset:33536
	ds_read_b128 v[190:193], v124 offset:33024
	ds_read_b128 v[194:197], v124 offset:33040
	ds_read_b128 v[144:147], v124 offset:32256
	ds_read_b128 v[148:151], v124 offset:32272
	v_pk_mul_f32 v[68:69], v[68:69], v[142:143] op_sel_hi:[1,0]
	v_pk_mul_f32 v[70:71], v[70:71], v[142:143] op_sel_hi:[1,0]
	s_mov_b32 vcc_lo, 0x8080808
	v_pk_mul_f32 v[56:57], v[56:57], v[142:143] op_sel_hi:[1,0]
	v_pk_mul_f32 v[58:59], v[58:59], v[142:143] op_sel_hi:[1,0]
	s_mov_b32 vcc_hi, 0x8080808
	v_pk_fma_f32 v[64:65], v[64:65], v[0:1], v[68:69] op_sel_hi:[1,0,1] neg_lo:[0,0,1] neg_hi:[0,0,1]
	v_pk_fma_f32 v[66:67], v[66:67], v[0:1], v[70:71] op_sel_hi:[1,0,1] neg_lo:[0,0,1] neg_hi:[0,0,1]
	v_cndmask_b32_e32 v132, v132, v143, vcc
	v_pk_fma_f32 v[60:61], v[60:61], v[0:1], v[56:57] op_sel_hi:[1,0,1] neg_lo:[0,0,1] neg_hi:[0,0,1]
	v_pk_fma_f32 v[62:63], v[62:63], v[0:1], v[58:59] op_sel_hi:[1,0,1] neg_lo:[0,0,1] neg_hi:[0,0,1]
	ds_read_b128 v[202:205], v124 offset:33296
	ds_read_b128 v[198:201], v124 offset:33280
	v_pk_fma_f32 v[36:37], v[36:37], v[48:49], v[64:65]
	v_pk_fma_f32 v[38:39], v[38:39], v[50:51], v[66:67]
	v_pk_fma_f32 v[32:33], v[32:33], v[40:41], v[60:61]
	v_pk_fma_f32 v[34:35], v[34:35], v[42:43], v[62:63]
	s_waitcnt lgkmcnt(2)
	v_pk_mul_f32 v[156:157], v[32:33], v[156:157]
	v_pk_mul_f32 v[52:53], v[32:33], v[52:53]
	v_pk_mul_f32 v[158:159], v[34:35], v[158:159]
	v_pk_mul_f32 v[54:55], v[34:35], v[54:55]
	v_pk_fma_f32 v[152:153], v[36:37], v[152:153], v[156:157]
	v_pk_fma_f32 v[44:45], v[36:37], v[44:45], v[52:53]
	v_pk_fma_f32 v[154:155], v[38:39], v[154:155], v[158:159]
	v_pk_fma_f32 v[46:47], v[38:39], v[46:47], v[54:55]
	v_pk_add_f32 v[152:153], v[152:153], v[154:155]
	v_pk_add_f32 v[44:45], v[44:45], v[46:47]
	v_add_f32_e32 v142, v152, v153
	v_add_f32_e32 v143, v44, v45
	ds_read_b128 v[76:79], v124 offset:34064
	v_add_f32_dpp v142, v142, v142 quad_perm:[1,0,3,2] row_mask:0xf bank_mask:0xf bound_ctrl:1
	v_add_f32_dpp v143, v143, v143 quad_perm:[1,0,3,2] row_mask:0xf bank_mask:0xf bound_ctrl:1
	ds_read_b128 v[72:75], v124 offset:34048
	v_add_f32_dpp v142, v142, v142 quad_perm:[2,3,0,1] row_mask:0xf bank_mask:0xf bound_ctrl:1
	v_add_f32_dpp v143, v143, v143 quad_perm:[2,3,0,1] row_mask:0xf bank_mask:0xf bound_ctrl:1
	ds_read_b128 v[68:71], v124 offset:34304
	v_add_f32_dpp v142, v142, v142 row_half_mirror row_mask:0xf bank_mask:0xf bound_ctrl:1
	v_add_f32_dpp v143, v143, v143 row_half_mirror row_mask:0xf bank_mask:0xf bound_ctrl:1
	ds_read_b128 v[56:59], v124 offset:34320
	ds_read_b32 v0, v135 offset:35072
	ds_read_b128 v[64:67], v124 offset:34560
	ds_read_b128 v[60:63], v124 offset:34576
	ds_read_b128 v[48:51], v124 offset:33792
	ds_read_b128 v[40:43], v124 offset:33808
	v_pk_mul_f32 v[182:183], v[182:183], v[142:143] op_sel_hi:[1,0]
	v_pk_mul_f32 v[184:185], v[184:185], v[142:143] op_sel_hi:[1,0]
	s_mov_b32 vcc_lo, 0x10101010
	v_pk_mul_f32 v[186:187], v[186:187], v[142:143] op_sel_hi:[1,0]
	v_pk_mul_f32 v[188:189], v[188:189], v[142:143] op_sel_hi:[1,0]
	s_mov_b32 vcc_hi, 0x10101010
	v_pk_fma_f32 v[190:191], v[190:191], v[160:161], v[182:183] op_sel_hi:[1,0,1] neg_lo:[0,0,1] neg_hi:[0,0,1]
	v_pk_fma_f32 v[192:193], v[192:193], v[160:161], v[184:185] op_sel_hi:[1,0,1] neg_lo:[0,0,1] neg_hi:[0,0,1]
	v_cndmask_b32_e32 v132, v132, v143, vcc
	v_pk_fma_f32 v[194:195], v[194:195], v[160:161], v[186:187] op_sel_hi:[1,0,1] neg_lo:[0,0,1] neg_hi:[0,0,1]
	v_pk_fma_f32 v[196:197], v[196:197], v[160:161], v[188:189] op_sel_hi:[1,0,1] neg_lo:[0,0,1] neg_hi:[0,0,1]
	ds_read_b128 v[52:55], v124 offset:34832
	ds_read_b128 v[44:47], v124 offset:34816
	v_pk_fma_f32 v[36:37], v[36:37], v[144:145], v[190:191]
	v_pk_fma_f32 v[38:39], v[38:39], v[146:147], v[192:193]
	v_pk_fma_f32 v[32:33], v[32:33], v[148:149], v[194:195]
	v_pk_fma_f32 v[34:35], v[34:35], v[150:151], v[196:197]
	s_waitcnt lgkmcnt(2)
	v_pk_mul_f32 v[76:77], v[32:33], v[76:77]
	v_pk_mul_f32 v[202:203], v[32:33], v[202:203]
	v_pk_mul_f32 v[78:79], v[34:35], v[78:79]
	v_pk_mul_f32 v[204:205], v[34:35], v[204:205]
	v_pk_fma_f32 v[72:73], v[36:37], v[72:73], v[76:77]
	v_pk_fma_f32 v[198:199], v[36:37], v[198:199], v[202:203]
	v_pk_fma_f32 v[74:75], v[38:39], v[74:75], v[78:79]
	v_pk_fma_f32 v[200:201], v[38:39], v[200:201], v[204:205]
	v_pk_add_f32 v[72:73], v[72:73], v[74:75]
	v_pk_add_f32 v[198:199], v[198:199], v[200:201]
	v_add_f32_e32 v142, v72, v73
	v_add_f32_e32 v143, v198, v199
	ds_read_b128 v[156:159], v124 offset:35600
	v_add_f32_dpp v142, v142, v142 quad_perm:[1,0,3,2] row_mask:0xf bank_mask:0xf bound_ctrl:1
	v_add_f32_dpp v143, v143, v143 quad_perm:[1,0,3,2] row_mask:0xf bank_mask:0xf bound_ctrl:1
	ds_read_b128 v[152:155], v124 offset:35584
	v_add_f32_dpp v142, v142, v142 quad_perm:[2,3,0,1] row_mask:0xf bank_mask:0xf bound_ctrl:1
	v_add_f32_dpp v143, v143, v143 quad_perm:[2,3,0,1] row_mask:0xf bank_mask:0xf bound_ctrl:1
	ds_read_b128 v[182:185], v124 offset:35840
	v_add_f32_dpp v142, v142, v142 row_half_mirror row_mask:0xf bank_mask:0xf bound_ctrl:1
	v_add_f32_dpp v143, v143, v143 row_half_mirror row_mask:0xf bank_mask:0xf bound_ctrl:1
	ds_read_b128 v[186:189], v124 offset:35856
	ds_read_b32 v160, v135 offset:36608
	ds_read_b128 v[190:193], v124 offset:36096
	ds_read_b128 v[194:197], v124 offset:36112
	ds_read_b128 v[144:147], v124 offset:35328
	ds_read_b128 v[148:151], v124 offset:35344
	v_pk_mul_f32 v[68:69], v[68:69], v[142:143] op_sel_hi:[1,0]
	v_pk_mul_f32 v[70:71], v[70:71], v[142:143] op_sel_hi:[1,0]
	s_mov_b32 vcc_lo, 0x20202020
	v_pk_mul_f32 v[56:57], v[56:57], v[142:143] op_sel_hi:[1,0]
	v_pk_mul_f32 v[58:59], v[58:59], v[142:143] op_sel_hi:[1,0]
	s_mov_b32 vcc_hi, 0x20202020
	v_pk_fma_f32 v[64:65], v[64:65], v[0:1], v[68:69] op_sel_hi:[1,0,1] neg_lo:[0,0,1] neg_hi:[0,0,1]
	v_pk_fma_f32 v[66:67], v[66:67], v[0:1], v[70:71] op_sel_hi:[1,0,1] neg_lo:[0,0,1] neg_hi:[0,0,1]
	v_cndmask_b32_e32 v132, v132, v143, vcc
	v_pk_fma_f32 v[60:61], v[60:61], v[0:1], v[56:57] op_sel_hi:[1,0,1] neg_lo:[0,0,1] neg_hi:[0,0,1]
	v_pk_fma_f32 v[62:63], v[62:63], v[0:1], v[58:59] op_sel_hi:[1,0,1] neg_lo:[0,0,1] neg_hi:[0,0,1]
	ds_read_b128 v[202:205], v124 offset:36368
	ds_read_b128 v[198:201], v124 offset:36352
	v_pk_fma_f32 v[36:37], v[36:37], v[48:49], v[64:65]
	v_pk_fma_f32 v[38:39], v[38:39], v[50:51], v[66:67]
	v_pk_fma_f32 v[32:33], v[32:33], v[40:41], v[60:61]
	v_pk_fma_f32 v[34:35], v[34:35], v[42:43], v[62:63]
	s_waitcnt lgkmcnt(2)
	v_pk_mul_f32 v[156:157], v[32:33], v[156:157]
	v_pk_mul_f32 v[52:53], v[32:33], v[52:53]
	v_pk_mul_f32 v[158:159], v[34:35], v[158:159]
	v_pk_mul_f32 v[54:55], v[34:35], v[54:55]
	v_pk_fma_f32 v[152:153], v[36:37], v[152:153], v[156:157]
	v_pk_fma_f32 v[44:45], v[36:37], v[44:45], v[52:53]
	v_pk_fma_f32 v[154:155], v[38:39], v[154:155], v[158:159]
	v_pk_fma_f32 v[46:47], v[38:39], v[46:47], v[54:55]
	v_pk_add_f32 v[152:153], v[152:153], v[154:155]
	v_pk_add_f32 v[44:45], v[44:45], v[46:47]
	v_add_f32_e32 v142, v152, v153
	v_add_f32_e32 v143, v44, v45
	ds_read_b128 v[76:79], v124 offset:37136
	v_add_f32_dpp v142, v142, v142 quad_perm:[1,0,3,2] row_mask:0xf bank_mask:0xf bound_ctrl:1
	v_add_f32_dpp v143, v143, v143 quad_perm:[1,0,3,2] row_mask:0xf bank_mask:0xf bound_ctrl:1
	ds_read_b128 v[72:75], v124 offset:37120
	v_add_f32_dpp v142, v142, v142 quad_perm:[2,3,0,1] row_mask:0xf bank_mask:0xf bound_ctrl:1
	v_add_f32_dpp v143, v143, v143 quad_perm:[2,3,0,1] row_mask:0xf bank_mask:0xf bound_ctrl:1
	ds_read_b128 v[68:71], v124 offset:37376
	v_add_f32_dpp v142, v142, v142 row_half_mirror row_mask:0xf bank_mask:0xf bound_ctrl:1
	v_add_f32_dpp v143, v143, v143 row_half_mirror row_mask:0xf bank_mask:0xf bound_ctrl:1
	ds_read_b128 v[56:59], v124 offset:37392
	ds_read_b32 v0, v135 offset:38144
	ds_read_b128 v[64:67], v124 offset:37632
	ds_read_b128 v[60:63], v124 offset:37648
	ds_read_b128 v[48:51], v124 offset:36864
	ds_read_b128 v[40:43], v124 offset:36880
	v_pk_mul_f32 v[182:183], v[182:183], v[142:143] op_sel_hi:[1,0]
	v_pk_mul_f32 v[184:185], v[184:185], v[142:143] op_sel_hi:[1,0]
	s_mov_b32 vcc_lo, 0x40404040
	v_pk_mul_f32 v[186:187], v[186:187], v[142:143] op_sel_hi:[1,0]
	v_pk_mul_f32 v[188:189], v[188:189], v[142:143] op_sel_hi:[1,0]
	s_mov_b32 vcc_hi, 0x40404040
	v_pk_fma_f32 v[190:191], v[190:191], v[160:161], v[182:183] op_sel_hi:[1,0,1] neg_lo:[0,0,1] neg_hi:[0,0,1]
	v_pk_fma_f32 v[192:193], v[192:193], v[160:161], v[184:185] op_sel_hi:[1,0,1] neg_lo:[0,0,1] neg_hi:[0,0,1]
	v_cndmask_b32_e32 v132, v132, v143, vcc
	v_pk_fma_f32 v[194:195], v[194:195], v[160:161], v[186:187] op_sel_hi:[1,0,1] neg_lo:[0,0,1] neg_hi:[0,0,1]
	v_pk_fma_f32 v[196:197], v[196:197], v[160:161], v[188:189] op_sel_hi:[1,0,1] neg_lo:[0,0,1] neg_hi:[0,0,1]
	ds_read_b128 v[52:55], v124 offset:37904
	ds_read_b128 v[44:47], v124 offset:37888
	v_pk_fma_f32 v[36:37], v[36:37], v[144:145], v[190:191]
	v_pk_fma_f32 v[38:39], v[38:39], v[146:147], v[192:193]
	v_pk_fma_f32 v[32:33], v[32:33], v[148:149], v[194:195]
	v_pk_fma_f32 v[34:35], v[34:35], v[150:151], v[196:197]
	s_waitcnt lgkmcnt(2)
	v_pk_mul_f32 v[76:77], v[32:33], v[76:77]
	v_pk_mul_f32 v[202:203], v[32:33], v[202:203]
	v_pk_mul_f32 v[78:79], v[34:35], v[78:79]
	v_pk_mul_f32 v[204:205], v[34:35], v[204:205]
	v_pk_fma_f32 v[72:73], v[36:37], v[72:73], v[76:77]
	v_pk_fma_f32 v[198:199], v[36:37], v[198:199], v[202:203]
	v_pk_fma_f32 v[74:75], v[38:39], v[74:75], v[78:79]
	v_pk_fma_f32 v[200:201], v[38:39], v[200:201], v[204:205]
	v_pk_add_f32 v[72:73], v[72:73], v[74:75]
	v_pk_add_f32 v[198:199], v[198:199], v[200:201]
	v_add_f32_e32 v142, v72, v73
	v_add_f32_e32 v143, v198, v199
	ds_read_b128 v[156:159], v124 offset:38672
	v_add_f32_dpp v142, v142, v142 quad_perm:[1,0,3,2] row_mask:0xf bank_mask:0xf bound_ctrl:1
	v_add_f32_dpp v143, v143, v143 quad_perm:[1,0,3,2] row_mask:0xf bank_mask:0xf bound_ctrl:1
	ds_read_b128 v[152:155], v124 offset:38656
	v_add_f32_dpp v142, v142, v142 quad_perm:[2,3,0,1] row_mask:0xf bank_mask:0xf bound_ctrl:1
	v_add_f32_dpp v143, v143, v143 quad_perm:[2,3,0,1] row_mask:0xf bank_mask:0xf bound_ctrl:1
	ds_read_b128 v[182:185], v124 offset:38912
	v_add_f32_dpp v142, v142, v142 row_half_mirror row_mask:0xf bank_mask:0xf bound_ctrl:1
	v_add_f32_dpp v143, v143, v143 row_half_mirror row_mask:0xf bank_mask:0xf bound_ctrl:1
	ds_read_b128 v[186:189], v124 offset:38928
	ds_read_b32 v160, v135 offset:39680
	ds_read_b128 v[190:193], v124 offset:39168
	ds_read_b128 v[194:197], v124 offset:39184
	ds_read_b128 v[144:147], v124 offset:38400
	ds_read_b128 v[148:151], v124 offset:38416
	v_pk_mul_f32 v[68:69], v[68:69], v[142:143] op_sel_hi:[1,0]
	v_pk_mul_f32 v[70:71], v[70:71], v[142:143] op_sel_hi:[1,0]
	s_mov_b32 vcc_lo, 0x80808080
	v_pk_mul_f32 v[56:57], v[56:57], v[142:143] op_sel_hi:[1,0]
	v_pk_mul_f32 v[58:59], v[58:59], v[142:143] op_sel_hi:[1,0]
	s_mov_b32 vcc_hi, 0x80808080
	v_pk_fma_f32 v[64:65], v[64:65], v[0:1], v[68:69] op_sel_hi:[1,0,1] neg_lo:[0,0,1] neg_hi:[0,0,1]
	v_pk_fma_f32 v[66:67], v[66:67], v[0:1], v[70:71] op_sel_hi:[1,0,1] neg_lo:[0,0,1] neg_hi:[0,0,1]
	v_cndmask_b32_e32 v132, v132, v143, vcc
	v_pk_fma_f32 v[60:61], v[60:61], v[0:1], v[56:57] op_sel_hi:[1,0,1] neg_lo:[0,0,1] neg_hi:[0,0,1]
	v_pk_fma_f32 v[62:63], v[62:63], v[0:1], v[58:59] op_sel_hi:[1,0,1] neg_lo:[0,0,1] neg_hi:[0,0,1]
	ds_read_b128 v[202:205], v124 offset:39440
	ds_read_b128 v[198:201], v124 offset:39424
	v_pk_fma_f32 v[36:37], v[36:37], v[48:49], v[64:65]
	v_pk_fma_f32 v[38:39], v[38:39], v[50:51], v[66:67]
	v_pk_fma_f32 v[32:33], v[32:33], v[40:41], v[60:61]
	v_pk_fma_f32 v[34:35], v[34:35], v[42:43], v[62:63]
	s_waitcnt lgkmcnt(2)
	v_pk_mul_f32 v[156:157], v[32:33], v[156:157]
	v_pk_mul_f32 v[52:53], v[32:33], v[52:53]
	v_pk_mul_f32 v[158:159], v[34:35], v[158:159]
	v_pk_mul_f32 v[54:55], v[34:35], v[54:55]
	v_pk_fma_f32 v[152:153], v[36:37], v[152:153], v[156:157]
	v_pk_fma_f32 v[44:45], v[36:37], v[44:45], v[52:53]
	v_pk_fma_f32 v[154:155], v[38:39], v[154:155], v[158:159]
	v_pk_fma_f32 v[46:47], v[38:39], v[46:47], v[54:55]
	v_pk_add_f32 v[152:153], v[152:153], v[154:155]
	v_pk_add_f32 v[44:45], v[44:45], v[46:47]
	v_add_f32_e32 v142, v152, v153
	v_add_f32_e32 v143, v44, v45
	ds_read_b128 v[76:79], v124 offset:40208
	v_add_f32_dpp v142, v142, v142 quad_perm:[1,0,3,2] row_mask:0xf bank_mask:0xf bound_ctrl:1
	v_add_f32_dpp v143, v143, v143 quad_perm:[1,0,3,2] row_mask:0xf bank_mask:0xf bound_ctrl:1
	ds_read_b128 v[72:75], v124 offset:40192
	v_add_f32_dpp v142, v142, v142 quad_perm:[2,3,0,1] row_mask:0xf bank_mask:0xf bound_ctrl:1
	v_add_f32_dpp v143, v143, v143 quad_perm:[2,3,0,1] row_mask:0xf bank_mask:0xf bound_ctrl:1
	ds_read_b128 v[68:71], v124 offset:40448
	v_add_f32_dpp v142, v142, v142 row_half_mirror row_mask:0xf bank_mask:0xf bound_ctrl:1
	v_add_f32_dpp v143, v143, v143 row_half_mirror row_mask:0xf bank_mask:0xf bound_ctrl:1
	ds_read_b128 v[56:59], v124 offset:40464
	ds_read_b32 v0, v135 offset:41216
	ds_read_b128 v[64:67], v124 offset:40704
	ds_read_b128 v[60:63], v124 offset:40720
	ds_read_b128 v[48:51], v124 offset:39936
	ds_read_b128 v[40:43], v124 offset:39952
	v_pk_mul_f32 v[182:183], v[182:183], v[142:143] op_sel_hi:[1,0]
	v_pk_mul_f32 v[184:185], v[184:185], v[142:143] op_sel_hi:[1,0]
	s_mov_b32 vcc_lo, 0x1010101
	v_pk_mul_f32 v[186:187], v[186:187], v[142:143] op_sel_hi:[1,0]
	v_pk_mul_f32 v[188:189], v[188:189], v[142:143] op_sel_hi:[1,0]
	s_mov_b32 vcc_hi, 0x1010101
	v_pk_fma_f32 v[190:191], v[190:191], v[160:161], v[182:183] op_sel_hi:[1,0,1] neg_lo:[0,0,1] neg_hi:[0,0,1]
	v_pk_fma_f32 v[192:193], v[192:193], v[160:161], v[184:185] op_sel_hi:[1,0,1] neg_lo:[0,0,1] neg_hi:[0,0,1]
	v_cndmask_b32_e32 v131, v131, v143, vcc
	v_pk_fma_f32 v[194:195], v[194:195], v[160:161], v[186:187] op_sel_hi:[1,0,1] neg_lo:[0,0,1] neg_hi:[0,0,1]
	v_pk_fma_f32 v[196:197], v[196:197], v[160:161], v[188:189] op_sel_hi:[1,0,1] neg_lo:[0,0,1] neg_hi:[0,0,1]
	ds_read_b128 v[52:55], v124 offset:40976
	ds_read_b128 v[44:47], v124 offset:40960
	v_pk_fma_f32 v[36:37], v[36:37], v[144:145], v[190:191]
	v_pk_fma_f32 v[38:39], v[38:39], v[146:147], v[192:193]
	v_pk_fma_f32 v[32:33], v[32:33], v[148:149], v[194:195]
	v_pk_fma_f32 v[34:35], v[34:35], v[150:151], v[196:197]
	s_waitcnt lgkmcnt(2)
	v_pk_mul_f32 v[76:77], v[32:33], v[76:77]
	v_pk_mul_f32 v[202:203], v[32:33], v[202:203]
	v_pk_mul_f32 v[78:79], v[34:35], v[78:79]
	v_pk_mul_f32 v[204:205], v[34:35], v[204:205]
	v_pk_fma_f32 v[72:73], v[36:37], v[72:73], v[76:77]
	v_pk_fma_f32 v[198:199], v[36:37], v[198:199], v[202:203]
	v_pk_fma_f32 v[74:75], v[38:39], v[74:75], v[78:79]
	v_pk_fma_f32 v[200:201], v[38:39], v[200:201], v[204:205]
	v_pk_add_f32 v[72:73], v[72:73], v[74:75]
	v_pk_add_f32 v[198:199], v[198:199], v[200:201]
	v_add_f32_e32 v142, v72, v73
	v_add_f32_e32 v143, v198, v199
	ds_read_b128 v[156:159], v124 offset:41744
	v_add_f32_dpp v142, v142, v142 quad_perm:[1,0,3,2] row_mask:0xf bank_mask:0xf bound_ctrl:1
	v_add_f32_dpp v143, v143, v143 quad_perm:[1,0,3,2] row_mask:0xf bank_mask:0xf bound_ctrl:1
	ds_read_b128 v[152:155], v124 offset:41728
	v_add_f32_dpp v142, v142, v142 quad_perm:[2,3,0,1] row_mask:0xf bank_mask:0xf bound_ctrl:1
	v_add_f32_dpp v143, v143, v143 quad_perm:[2,3,0,1] row_mask:0xf bank_mask:0xf bound_ctrl:1
	ds_read_b128 v[182:185], v124 offset:41984
	v_add_f32_dpp v142, v142, v142 row_half_mirror row_mask:0xf bank_mask:0xf bound_ctrl:1
	v_add_f32_dpp v143, v143, v143 row_half_mirror row_mask:0xf bank_mask:0xf bound_ctrl:1
	ds_read_b128 v[186:189], v124 offset:42000
	ds_read_b32 v160, v135 offset:42752
	ds_read_b128 v[190:193], v124 offset:42240
	ds_read_b128 v[194:197], v124 offset:42256
	ds_read_b128 v[144:147], v124 offset:41472
	ds_read_b128 v[148:151], v124 offset:41488
	v_pk_mul_f32 v[68:69], v[68:69], v[142:143] op_sel_hi:[1,0]
	v_pk_mul_f32 v[70:71], v[70:71], v[142:143] op_sel_hi:[1,0]
	s_mov_b32 vcc_lo, 0x2020202
	v_pk_mul_f32 v[56:57], v[56:57], v[142:143] op_sel_hi:[1,0]
	v_pk_mul_f32 v[58:59], v[58:59], v[142:143] op_sel_hi:[1,0]
	s_mov_b32 vcc_hi, 0x2020202
	v_pk_fma_f32 v[64:65], v[64:65], v[0:1], v[68:69] op_sel_hi:[1,0,1] neg_lo:[0,0,1] neg_hi:[0,0,1]
	v_pk_fma_f32 v[66:67], v[66:67], v[0:1], v[70:71] op_sel_hi:[1,0,1] neg_lo:[0,0,1] neg_hi:[0,0,1]
	v_cndmask_b32_e32 v131, v131, v143, vcc
	v_pk_fma_f32 v[60:61], v[60:61], v[0:1], v[56:57] op_sel_hi:[1,0,1] neg_lo:[0,0,1] neg_hi:[0,0,1]
	v_pk_fma_f32 v[62:63], v[62:63], v[0:1], v[58:59] op_sel_hi:[1,0,1] neg_lo:[0,0,1] neg_hi:[0,0,1]
	ds_read_b128 v[202:205], v124 offset:42512
	ds_read_b128 v[198:201], v124 offset:42496
	v_pk_fma_f32 v[36:37], v[36:37], v[48:49], v[64:65]
	v_pk_fma_f32 v[38:39], v[38:39], v[50:51], v[66:67]
	v_pk_fma_f32 v[32:33], v[32:33], v[40:41], v[60:61]
	v_pk_fma_f32 v[34:35], v[34:35], v[42:43], v[62:63]
	s_waitcnt lgkmcnt(2)
	v_pk_mul_f32 v[156:157], v[32:33], v[156:157]
	v_pk_mul_f32 v[52:53], v[32:33], v[52:53]
	v_pk_mul_f32 v[158:159], v[34:35], v[158:159]
	v_pk_mul_f32 v[54:55], v[34:35], v[54:55]
	v_pk_fma_f32 v[152:153], v[36:37], v[152:153], v[156:157]
	v_pk_fma_f32 v[44:45], v[36:37], v[44:45], v[52:53]
	v_pk_fma_f32 v[154:155], v[38:39], v[154:155], v[158:159]
	v_pk_fma_f32 v[46:47], v[38:39], v[46:47], v[54:55]
	v_pk_add_f32 v[152:153], v[152:153], v[154:155]
	v_pk_add_f32 v[44:45], v[44:45], v[46:47]
	v_add_f32_e32 v142, v152, v153
	v_add_f32_e32 v143, v44, v45
	ds_read_b128 v[76:79], v124 offset:43280
	v_add_f32_dpp v142, v142, v142 quad_perm:[1,0,3,2] row_mask:0xf bank_mask:0xf bound_ctrl:1
	v_add_f32_dpp v143, v143, v143 quad_perm:[1,0,3,2] row_mask:0xf bank_mask:0xf bound_ctrl:1
	ds_read_b128 v[72:75], v124 offset:43264
	v_add_f32_dpp v142, v142, v142 quad_perm:[2,3,0,1] row_mask:0xf bank_mask:0xf bound_ctrl:1
	v_add_f32_dpp v143, v143, v143 quad_perm:[2,3,0,1] row_mask:0xf bank_mask:0xf bound_ctrl:1
	ds_read_b128 v[68:71], v124 offset:43520
	v_add_f32_dpp v142, v142, v142 row_half_mirror row_mask:0xf bank_mask:0xf bound_ctrl:1
	v_add_f32_dpp v143, v143, v143 row_half_mirror row_mask:0xf bank_mask:0xf bound_ctrl:1
	ds_read_b128 v[56:59], v124 offset:43536
	ds_read_b32 v0, v135 offset:44288
	ds_read_b128 v[64:67], v124 offset:43776
	ds_read_b128 v[60:63], v124 offset:43792
	ds_read_b128 v[48:51], v124 offset:43008
	ds_read_b128 v[40:43], v124 offset:43024
	v_pk_mul_f32 v[182:183], v[182:183], v[142:143] op_sel_hi:[1,0]
	v_pk_mul_f32 v[184:185], v[184:185], v[142:143] op_sel_hi:[1,0]
	s_mov_b32 vcc_lo, 0x4040404
	v_pk_mul_f32 v[186:187], v[186:187], v[142:143] op_sel_hi:[1,0]
	v_pk_mul_f32 v[188:189], v[188:189], v[142:143] op_sel_hi:[1,0]
	s_mov_b32 vcc_hi, 0x4040404
	v_pk_fma_f32 v[190:191], v[190:191], v[160:161], v[182:183] op_sel_hi:[1,0,1] neg_lo:[0,0,1] neg_hi:[0,0,1]
	v_pk_fma_f32 v[192:193], v[192:193], v[160:161], v[184:185] op_sel_hi:[1,0,1] neg_lo:[0,0,1] neg_hi:[0,0,1]
	v_cndmask_b32_e32 v131, v131, v143, vcc
	v_pk_fma_f32 v[194:195], v[194:195], v[160:161], v[186:187] op_sel_hi:[1,0,1] neg_lo:[0,0,1] neg_hi:[0,0,1]
	v_pk_fma_f32 v[196:197], v[196:197], v[160:161], v[188:189] op_sel_hi:[1,0,1] neg_lo:[0,0,1] neg_hi:[0,0,1]
	ds_read_b128 v[52:55], v124 offset:44048
	ds_read_b128 v[44:47], v124 offset:44032
	v_pk_fma_f32 v[36:37], v[36:37], v[144:145], v[190:191]
	v_pk_fma_f32 v[38:39], v[38:39], v[146:147], v[192:193]
	v_pk_fma_f32 v[32:33], v[32:33], v[148:149], v[194:195]
	v_pk_fma_f32 v[34:35], v[34:35], v[150:151], v[196:197]
	s_waitcnt lgkmcnt(2)
	v_pk_mul_f32 v[76:77], v[32:33], v[76:77]
	v_pk_mul_f32 v[202:203], v[32:33], v[202:203]
	v_pk_mul_f32 v[78:79], v[34:35], v[78:79]
	v_pk_mul_f32 v[204:205], v[34:35], v[204:205]
	v_pk_fma_f32 v[72:73], v[36:37], v[72:73], v[76:77]
	v_pk_fma_f32 v[198:199], v[36:37], v[198:199], v[202:203]
	v_pk_fma_f32 v[74:75], v[38:39], v[74:75], v[78:79]
	v_pk_fma_f32 v[200:201], v[38:39], v[200:201], v[204:205]
	v_pk_add_f32 v[72:73], v[72:73], v[74:75]
	v_pk_add_f32 v[198:199], v[198:199], v[200:201]
	v_add_f32_e32 v142, v72, v73
	v_add_f32_e32 v143, v198, v199
	ds_read_b128 v[156:159], v124 offset:44816
	v_add_f32_dpp v142, v142, v142 quad_perm:[1,0,3,2] row_mask:0xf bank_mask:0xf bound_ctrl:1
	v_add_f32_dpp v143, v143, v143 quad_perm:[1,0,3,2] row_mask:0xf bank_mask:0xf bound_ctrl:1
	ds_read_b128 v[152:155], v124 offset:44800
	v_add_f32_dpp v142, v142, v142 quad_perm:[2,3,0,1] row_mask:0xf bank_mask:0xf bound_ctrl:1
	v_add_f32_dpp v143, v143, v143 quad_perm:[2,3,0,1] row_mask:0xf bank_mask:0xf bound_ctrl:1
	ds_read_b128 v[182:185], v124 offset:45056
	v_add_f32_dpp v142, v142, v142 row_half_mirror row_mask:0xf bank_mask:0xf bound_ctrl:1
	v_add_f32_dpp v143, v143, v143 row_half_mirror row_mask:0xf bank_mask:0xf bound_ctrl:1
	ds_read_b128 v[186:189], v124 offset:45072
	ds_read_b32 v160, v135 offset:45824
	ds_read_b128 v[190:193], v124 offset:45312
	ds_read_b128 v[194:197], v124 offset:45328
	ds_read_b128 v[144:147], v124 offset:44544
	ds_read_b128 v[148:151], v124 offset:44560
	v_pk_mul_f32 v[68:69], v[68:69], v[142:143] op_sel_hi:[1,0]
	v_pk_mul_f32 v[70:71], v[70:71], v[142:143] op_sel_hi:[1,0]
	s_mov_b32 vcc_lo, 0x8080808
	v_pk_mul_f32 v[56:57], v[56:57], v[142:143] op_sel_hi:[1,0]
	v_pk_mul_f32 v[58:59], v[58:59], v[142:143] op_sel_hi:[1,0]
	s_mov_b32 vcc_hi, 0x8080808
	v_pk_fma_f32 v[64:65], v[64:65], v[0:1], v[68:69] op_sel_hi:[1,0,1] neg_lo:[0,0,1] neg_hi:[0,0,1]
	v_pk_fma_f32 v[66:67], v[66:67], v[0:1], v[70:71] op_sel_hi:[1,0,1] neg_lo:[0,0,1] neg_hi:[0,0,1]
	v_cndmask_b32_e32 v131, v131, v143, vcc
	v_pk_fma_f32 v[60:61], v[60:61], v[0:1], v[56:57] op_sel_hi:[1,0,1] neg_lo:[0,0,1] neg_hi:[0,0,1]
	v_pk_fma_f32 v[62:63], v[62:63], v[0:1], v[58:59] op_sel_hi:[1,0,1] neg_lo:[0,0,1] neg_hi:[0,0,1]
	ds_read_b128 v[202:205], v124 offset:45584
	ds_read_b128 v[198:201], v124 offset:45568
	v_pk_fma_f32 v[36:37], v[36:37], v[48:49], v[64:65]
	v_pk_fma_f32 v[38:39], v[38:39], v[50:51], v[66:67]
	v_pk_fma_f32 v[32:33], v[32:33], v[40:41], v[60:61]
	v_pk_fma_f32 v[34:35], v[34:35], v[42:43], v[62:63]
	s_waitcnt lgkmcnt(2)
	v_pk_mul_f32 v[156:157], v[32:33], v[156:157]
	v_pk_mul_f32 v[52:53], v[32:33], v[52:53]
	v_pk_mul_f32 v[158:159], v[34:35], v[158:159]
	v_pk_mul_f32 v[54:55], v[34:35], v[54:55]
	v_pk_fma_f32 v[152:153], v[36:37], v[152:153], v[156:157]
	v_pk_fma_f32 v[44:45], v[36:37], v[44:45], v[52:53]
	v_pk_fma_f32 v[154:155], v[38:39], v[154:155], v[158:159]
	v_pk_fma_f32 v[46:47], v[38:39], v[46:47], v[54:55]
	v_pk_add_f32 v[152:153], v[152:153], v[154:155]
	v_pk_add_f32 v[44:45], v[44:45], v[46:47]
	v_add_f32_e32 v142, v152, v153
	v_add_f32_e32 v143, v44, v45
	ds_read_b128 v[76:79], v124 offset:46352
	v_add_f32_dpp v142, v142, v142 quad_perm:[1,0,3,2] row_mask:0xf bank_mask:0xf bound_ctrl:1
	v_add_f32_dpp v143, v143, v143 quad_perm:[1,0,3,2] row_mask:0xf bank_mask:0xf bound_ctrl:1
	ds_read_b128 v[72:75], v124 offset:46336
	v_add_f32_dpp v142, v142, v142 quad_perm:[2,3,0,1] row_mask:0xf bank_mask:0xf bound_ctrl:1
	v_add_f32_dpp v143, v143, v143 quad_perm:[2,3,0,1] row_mask:0xf bank_mask:0xf bound_ctrl:1
	ds_read_b128 v[68:71], v124 offset:46592
	v_add_f32_dpp v142, v142, v142 row_half_mirror row_mask:0xf bank_mask:0xf bound_ctrl:1
	v_add_f32_dpp v143, v143, v143 row_half_mirror row_mask:0xf bank_mask:0xf bound_ctrl:1
	ds_read_b128 v[56:59], v124 offset:46608
	ds_read_b32 v0, v135 offset:47360
	ds_read_b128 v[64:67], v124 offset:46848
	ds_read_b128 v[60:63], v124 offset:46864
	ds_read_b128 v[48:51], v124 offset:46080
	ds_read_b128 v[40:43], v124 offset:46096
	v_pk_mul_f32 v[182:183], v[182:183], v[142:143] op_sel_hi:[1,0]
	v_pk_mul_f32 v[184:185], v[184:185], v[142:143] op_sel_hi:[1,0]
	s_mov_b32 vcc_lo, 0x10101010
	v_pk_mul_f32 v[186:187], v[186:187], v[142:143] op_sel_hi:[1,0]
	v_pk_mul_f32 v[188:189], v[188:189], v[142:143] op_sel_hi:[1,0]
	s_mov_b32 vcc_hi, 0x10101010
	v_pk_fma_f32 v[190:191], v[190:191], v[160:161], v[182:183] op_sel_hi:[1,0,1] neg_lo:[0,0,1] neg_hi:[0,0,1]
	v_pk_fma_f32 v[192:193], v[192:193], v[160:161], v[184:185] op_sel_hi:[1,0,1] neg_lo:[0,0,1] neg_hi:[0,0,1]
	v_cndmask_b32_e32 v131, v131, v143, vcc
	v_pk_fma_f32 v[194:195], v[194:195], v[160:161], v[186:187] op_sel_hi:[1,0,1] neg_lo:[0,0,1] neg_hi:[0,0,1]
	v_pk_fma_f32 v[196:197], v[196:197], v[160:161], v[188:189] op_sel_hi:[1,0,1] neg_lo:[0,0,1] neg_hi:[0,0,1]
	ds_read_b128 v[52:55], v124 offset:47120
	ds_read_b128 v[44:47], v124 offset:47104
	v_pk_fma_f32 v[36:37], v[36:37], v[144:145], v[190:191]
	v_pk_fma_f32 v[38:39], v[38:39], v[146:147], v[192:193]
	v_pk_fma_f32 v[32:33], v[32:33], v[148:149], v[194:195]
	v_pk_fma_f32 v[34:35], v[34:35], v[150:151], v[196:197]
	s_waitcnt lgkmcnt(2)
	v_pk_mul_f32 v[76:77], v[32:33], v[76:77]
	v_pk_mul_f32 v[202:203], v[32:33], v[202:203]
	v_pk_mul_f32 v[78:79], v[34:35], v[78:79]
	v_pk_mul_f32 v[204:205], v[34:35], v[204:205]
	v_pk_fma_f32 v[72:73], v[36:37], v[72:73], v[76:77]
	v_pk_fma_f32 v[198:199], v[36:37], v[198:199], v[202:203]
	v_pk_fma_f32 v[74:75], v[38:39], v[74:75], v[78:79]
	v_pk_fma_f32 v[200:201], v[38:39], v[200:201], v[204:205]
	v_pk_add_f32 v[72:73], v[72:73], v[74:75]
	v_pk_add_f32 v[198:199], v[198:199], v[200:201]
	v_add_f32_e32 v142, v72, v73
	v_add_f32_e32 v143, v198, v199
	ds_read_b128 v[156:159], v124 offset:47888
	v_add_f32_dpp v142, v142, v142 quad_perm:[1,0,3,2] row_mask:0xf bank_mask:0xf bound_ctrl:1
	v_add_f32_dpp v143, v143, v143 quad_perm:[1,0,3,2] row_mask:0xf bank_mask:0xf bound_ctrl:1
	ds_read_b128 v[152:155], v124 offset:47872
	v_add_f32_dpp v142, v142, v142 quad_perm:[2,3,0,1] row_mask:0xf bank_mask:0xf bound_ctrl:1
	v_add_f32_dpp v143, v143, v143 quad_perm:[2,3,0,1] row_mask:0xf bank_mask:0xf bound_ctrl:1
	ds_read_b128 v[182:185], v124 offset:48128
	v_add_f32_dpp v142, v142, v142 row_half_mirror row_mask:0xf bank_mask:0xf bound_ctrl:1
	v_add_f32_dpp v143, v143, v143 row_half_mirror row_mask:0xf bank_mask:0xf bound_ctrl:1
	ds_read_b128 v[186:189], v124 offset:48144
	ds_read_b32 v160, v135 offset:48896
	ds_read_b128 v[190:193], v124 offset:48384
	ds_read_b128 v[194:197], v124 offset:48400
	ds_read_b128 v[144:147], v124 offset:47616
	ds_read_b128 v[148:151], v124 offset:47632
	v_pk_mul_f32 v[68:69], v[68:69], v[142:143] op_sel_hi:[1,0]
	v_pk_mul_f32 v[70:71], v[70:71], v[142:143] op_sel_hi:[1,0]
	s_mov_b32 vcc_lo, 0x20202020
	v_pk_mul_f32 v[56:57], v[56:57], v[142:143] op_sel_hi:[1,0]
	v_pk_mul_f32 v[58:59], v[58:59], v[142:143] op_sel_hi:[1,0]
	s_mov_b32 vcc_hi, 0x20202020
	v_pk_fma_f32 v[64:65], v[64:65], v[0:1], v[68:69] op_sel_hi:[1,0,1] neg_lo:[0,0,1] neg_hi:[0,0,1]
	v_pk_fma_f32 v[66:67], v[66:67], v[0:1], v[70:71] op_sel_hi:[1,0,1] neg_lo:[0,0,1] neg_hi:[0,0,1]
	v_cndmask_b32_e32 v131, v131, v143, vcc
	v_pk_fma_f32 v[60:61], v[60:61], v[0:1], v[56:57] op_sel_hi:[1,0,1] neg_lo:[0,0,1] neg_hi:[0,0,1]
	v_pk_fma_f32 v[62:63], v[62:63], v[0:1], v[58:59] op_sel_hi:[1,0,1] neg_lo:[0,0,1] neg_hi:[0,0,1]
	ds_read_b128 v[202:205], v124 offset:48656
	ds_read_b128 v[198:201], v124 offset:48640
	v_pk_fma_f32 v[36:37], v[36:37], v[48:49], v[64:65]
	v_pk_fma_f32 v[38:39], v[38:39], v[50:51], v[66:67]
	v_pk_fma_f32 v[32:33], v[32:33], v[40:41], v[60:61]
	v_pk_fma_f32 v[34:35], v[34:35], v[42:43], v[62:63]
	s_waitcnt lgkmcnt(2)
	v_pk_mul_f32 v[156:157], v[32:33], v[156:157]
	v_pk_mul_f32 v[52:53], v[32:33], v[52:53]
	v_pk_mul_f32 v[158:159], v[34:35], v[158:159]
	v_pk_mul_f32 v[54:55], v[34:35], v[54:55]
	v_pk_fma_f32 v[152:153], v[36:37], v[152:153], v[156:157]
	v_pk_fma_f32 v[44:45], v[36:37], v[44:45], v[52:53]
	v_pk_fma_f32 v[154:155], v[38:39], v[154:155], v[158:159]
	v_pk_fma_f32 v[46:47], v[38:39], v[46:47], v[54:55]
	v_pk_add_f32 v[152:153], v[152:153], v[154:155]
	v_pk_add_f32 v[44:45], v[44:45], v[46:47]
	v_add_f32_e32 v142, v152, v153
	v_add_f32_e32 v143, v44, v45
	s_nop 0
	v_add_f32_dpp v142, v142, v142 quad_perm:[1,0,3,2] row_mask:0xf bank_mask:0xf bound_ctrl:1
	v_add_f32_dpp v143, v143, v143 quad_perm:[1,0,3,2] row_mask:0xf bank_mask:0xf bound_ctrl:1
	s_nop 0
	v_add_f32_dpp v142, v142, v142 quad_perm:[2,3,0,1] row_mask:0xf bank_mask:0xf bound_ctrl:1
	v_add_f32_dpp v143, v143, v143 quad_perm:[2,3,0,1] row_mask:0xf bank_mask:0xf bound_ctrl:1
	s_nop 0
	v_add_f32_dpp v142, v142, v142 row_half_mirror row_mask:0xf bank_mask:0xf bound_ctrl:1
	v_add_f32_dpp v143, v143, v143 row_half_mirror row_mask:0xf bank_mask:0xf bound_ctrl:1
	v_pk_mul_f32 v[182:183], v[182:183], v[142:143] op_sel_hi:[1,0]
	v_pk_mul_f32 v[184:185], v[184:185], v[142:143] op_sel_hi:[1,0]
	s_mov_b32 vcc_lo, 0x40404040
	v_pk_mul_f32 v[186:187], v[186:187], v[142:143] op_sel_hi:[1,0]
	v_pk_mul_f32 v[188:189], v[188:189], v[142:143] op_sel_hi:[1,0]
	s_mov_b32 vcc_hi, 0x40404040
	v_pk_fma_f32 v[190:191], v[190:191], v[160:161], v[182:183] op_sel_hi:[1,0,1] neg_lo:[0,0,1] neg_hi:[0,0,1]
	v_pk_fma_f32 v[192:193], v[192:193], v[160:161], v[184:185] op_sel_hi:[1,0,1] neg_lo:[0,0,1] neg_hi:[0,0,1]
	v_cndmask_b32_e32 v131, v131, v143, vcc
	v_pk_fma_f32 v[194:195], v[194:195], v[160:161], v[186:187] op_sel_hi:[1,0,1] neg_lo:[0,0,1] neg_hi:[0,0,1]
	v_pk_fma_f32 v[196:197], v[196:197], v[160:161], v[188:189] op_sel_hi:[1,0,1] neg_lo:[0,0,1] neg_hi:[0,0,1]
	v_pk_fma_f32 v[36:37], v[36:37], v[144:145], v[190:191]
	v_pk_fma_f32 v[38:39], v[38:39], v[146:147], v[192:193]
	v_pk_fma_f32 v[32:33], v[32:33], v[148:149], v[194:195]
	v_pk_fma_f32 v[34:35], v[34:35], v[150:151], v[196:197]
	s_waitcnt lgkmcnt(0)
	v_pk_mul_f32 v[202:203], v[32:33], v[202:203]
	v_pk_mul_f32 v[204:205], v[34:35], v[204:205]
	v_pk_fma_f32 v[198:199], v[36:37], v[198:199], v[202:203]
	v_pk_fma_f32 v[200:201], v[38:39], v[200:201], v[204:205]
	v_pk_add_f32 v[198:199], v[198:199], v[200:201]
	v_add_f32_e32 v143, v198, v199
	s_nop 1
	v_add_f32_dpp v143, v143, v143 quad_perm:[1,0,3,2] row_mask:0xf bank_mask:0xf bound_ctrl:1
	s_nop 1
	v_add_f32_dpp v143, v143, v143 quad_perm:[2,3,0,1] row_mask:0xf bank_mask:0xf bound_ctrl:1
	s_nop 1
	v_add_f32_dpp v143, v143, v143 row_half_mirror row_mask:0xf bank_mask:0xf bound_ctrl:1
	s_mov_b32 vcc_lo, 0x80808080
	s_mov_b32 vcc_hi, 0x80808080
	v_cndmask_b32_e32 v131, v131, v143, vcc
	s_setprio 0
	s_lshl_b32 s70, s64, 5
	s_add_u32 s70, s70, s4
	v_add_u32_e32 v40, s70, v86
	v_lshlrev_b32_e32 v46, 1, v112
	v_mul_u32_u24_e32 v41, 0xc00, v40
	v_add_u32_e32 v41, v41, v46
	v_lshl_add_u32 v42, v40, 10, v46
	s_and_b32 s71, s64, 1
	s_lshl_b32 s71, s71, 7
	s_add_u32 s71, s71, 0x18000
	v_lshl_add_u32 v43, v86, 2, s71
	v_mov_b32_e32 v44, 0x600
	v_mad_u32_u24 v44, v86, v44, v135
	ds_read_b32 v48, v43
	ds_read_b32 v49, v43 offset:32
	ds_read_b32 v50, v43 offset:64
	ds_read_b32 v51, v43 offset:96
	ds_read_b32 v52, v44 offset:1280
	ds_read_b32 v53, v44 offset:13568
	ds_read_b32 v54, v44 offset:25856
	ds_read_b32 v55, v44 offset:38144
	v_bfe_u32 v47, v134, 16, 1
	v_add3_u32 v47, v134, v47, s78
	global_store_short_d16_hi v41, v47, s[60:61]
	v_bfe_u32 v47, v133, 16, 1
	v_add3_u32 v47, v133, v47, s78
	v_add_u32_e32 v45, 0x6000, v41
	global_store_short_d16_hi v45, v47, s[60:61]
	v_bfe_u32 v47, v132, 16, 1
	v_add3_u32 v47, v132, v47, s78
	v_add_u32_e32 v45, 0xc000, v41
	global_store_short_d16_hi v45, v47, s[60:61]
	v_bfe_u32 v47, v131, 16, 1
	v_add3_u32 v47, v131, v47, s78
	v_add_u32_e32 v45, 0x12000, v41
	global_store_short_d16_hi v45, v47, s[60:61]
	s_waitcnt lgkmcnt(0)
	v_mul_f32_e32 v47, v48, v52
	v_bfe_u32 v56, v47, 16, 1
	v_add3_u32 v47, v47, v56, s78
	global_store_short_d16_hi v42, v47, s[44:45]
	v_mul_f32_e32 v47, v49, v53
	v_bfe_u32 v56, v47, 16, 1
	v_add3_u32 v47, v47, v56, s78
	v_add_u32_e32 v45, 0x2000, v42
	global_store_short_d16_hi v45, v47, s[44:45]
	v_mul_f32_e32 v47, v50, v54
	v_bfe_u32 v56, v47, 16, 1
	v_add3_u32 v47, v47, v56, s78
	v_add_u32_e32 v45, 0x4000, v42
	global_store_short_d16_hi v45, v47, s[44:45]
	v_mul_f32_e32 v47, v51, v55
	v_bfe_u32 v56, v47, 16, 1
	v_add3_u32 v47, v47, v56, s78
	v_add_u32_e32 v45, 0x6000, v42
	global_store_short_d16_hi v45, v47, s[44:45]
	s_branch .LBB0_631
